# GEMM K-loops: late A DMAs in the two MFMA groups directly before the barrier (groups 5-6 instead of 4-5)
# speedup vs baseline: 1.0133x; 1.0133x over previous
.Lg161_loop:
	s_add_u32 s51, s50, 0x10000
	s_sub_u32 s53, s51, 0x28000
	s_cmp_ge_u32 s51, 0x28000
	s_cselect_b32 s51, s53, s51
	s_add_u32 s52, s49, 0x20000
	s_sub_u32 s53, s52, 0x28000
	s_cmp_ge_u32 s52, 0x28000
	s_cselect_b32 s52, s53, s52
	v_add_u32_e32 v137, s50, v135
	s_waitcnt lgkmcnt(4)
	s_waitcnt lgkmcnt(3)
	v_mfma_f32_16x16x32_bf16 v[112:115], v[164:167], v[224:227], v[112:115]
	v_mfma_f32_16x16x32_bf16 v[120:123], v[168:171], v[224:227], v[120:123]
	v_mfma_f32_16x16x32_bf16 v[96:99], v[172:175], v[224:227], v[96:99]
	v_mfma_f32_16x16x32_bf16 v[104:107], v[176:179], v[224:227], v[104:107]
	s_add_u32 m0, s51, s48
	s_nop 0
	global_load_lds_dwordx4 v139, s[64:65]
	s_add_u32 s64, s64, 0x80
	s_addc_u32 s65, s65, 0
	s_add_u32 s53, s51, s48
	s_add_u32 m0, s53, 0x2000
	s_nop 0
	global_load_lds_dwordx4 v139, s[66:67]
	s_add_u32 s66, s66, 0x80
	s_addc_u32 s67, s67, 0
	ds_read_b128 v[224:227], v136 offset:8192
	ds_read_b128 v[180:183], v137
	s_waitcnt lgkmcnt(4)
	v_mfma_f32_16x16x32_bf16 v[116:119], v[164:167], v[228:231], v[116:119]
	v_mfma_f32_16x16x32_bf16 v[124:127], v[168:171], v[228:231], v[124:127]
	v_mfma_f32_16x16x32_bf16 v[100:103], v[172:175], v[228:231], v[100:103]
	v_mfma_f32_16x16x32_bf16 v[108:111], v[176:179], v[228:231], v[108:111]
	s_add_u32 s53, s51, s48
	s_add_u32 m0, s53, 0x4000
	s_nop 0
	global_load_lds_dwordx4 v139, s[68:69]
	s_add_u32 s68, s68, 0x80
	s_addc_u32 s69, s69, 0
	s_add_u32 s53, s51, s48
	s_add_u32 m0, s53, 0x6000
	s_nop 0
	global_load_lds_dwordx4 v139, s[70:71]
	s_add_u32 s70, s70, 0x80
	s_addc_u32 s71, s71, 0
	ds_read_b128 v[228:231], v136 offset:10240
	ds_read_b128 v[212:215], v137 offset:2048
	s_waitcnt lgkmcnt(5)
	v_mfma_f32_16x16x32_bf16 v[80:83], v[164:167], v[232:235], v[80:83]
	v_mfma_f32_16x16x32_bf16 v[88:91], v[168:171], v[232:235], v[88:91]
	v_mfma_f32_16x16x32_bf16 v[64:67], v[172:175], v[232:235], v[64:67]
	v_mfma_f32_16x16x32_bf16 v[72:75], v[176:179], v[232:235], v[72:75]
	ds_read_b128 v[232:235], v136 offset:12288
	ds_read_b128 v[216:219], v137 offset:4096
	s_waitcnt lgkmcnt(6)
	v_mfma_f32_16x16x32_bf16 v[84:87], v[164:167], v[236:239], v[84:87]
	v_mfma_f32_16x16x32_bf16 v[92:95], v[168:171], v[236:239], v[92:95]
	v_mfma_f32_16x16x32_bf16 v[68:71], v[172:175], v[236:239], v[68:71]
	v_mfma_f32_16x16x32_bf16 v[76:79], v[176:179], v[236:239], v[76:79]
	ds_read_b128 v[236:239], v136 offset:14336
	ds_read_b128 v[220:223], v137 offset:6144
	v_add_u32_e32 v136, s49, v133
	s_waitcnt lgkmcnt(7)
	v_mfma_f32_16x16x32_bf16 v[48:51], v[164:167], v[224:227], v[48:51]
	v_mfma_f32_16x16x32_bf16 v[56:59], v[168:171], v[224:227], v[56:59]
	v_mfma_f32_16x16x32_bf16 v[32:35], v[172:175], v[224:227], v[32:35]
	v_mfma_f32_16x16x32_bf16 v[40:43], v[176:179], v[224:227], v[40:43]
	ds_read_b128 v[224:227], v136
	s_waitcnt lgkmcnt(6)
	v_mfma_f32_16x16x32_bf16 v[52:55], v[164:167], v[228:231], v[52:55]
	v_mfma_f32_16x16x32_bf16 v[60:63], v[168:171], v[228:231], v[60:63]
	v_mfma_f32_16x16x32_bf16 v[36:39], v[172:175], v[228:231], v[36:39]
	v_mfma_f32_16x16x32_bf16 v[44:47], v[176:179], v[228:231], v[44:47]
	ds_read_b128 v[228:231], v136 offset:2048
	s_waitcnt lgkmcnt(5)
	v_mfma_f32_16x16x32_bf16 v[16:19], v[164:167], v[232:235], v[16:19]
	v_mfma_f32_16x16x32_bf16 v[24:27], v[168:171], v[232:235], v[24:27]
	v_mfma_f32_16x16x32_bf16 v[0:3], v[172:175], v[232:235], v[0:3]
	v_mfma_f32_16x16x32_bf16 v[8:11], v[176:179], v[232:235], v[8:11]
	ds_read_b128 v[232:235], v136 offset:4096
	s_waitcnt lgkmcnt(4)
	v_mfma_f32_16x16x32_bf16 v[20:23], v[164:167], v[236:239], v[20:23]
	v_mfma_f32_16x16x32_bf16 v[28:31], v[168:171], v[236:239], v[28:31]
	v_mfma_f32_16x16x32_bf16 v[4:7], v[172:175], v[236:239], v[4:7]
	v_mfma_f32_16x16x32_bf16 v[12:15], v[176:179], v[236:239], v[12:15]
	ds_read_b128 v[236:239], v136 offset:6144
	s_waitcnt lgkmcnt(4)
	s_waitcnt lgkmcnt(3)
	v_mfma_f32_16x16x32_bf16 v[112:115], v[180:183], v[224:227], v[112:115]
	v_mfma_f32_16x16x32_bf16 v[120:123], v[212:215], v[224:227], v[120:123]
	v_mfma_f32_16x16x32_bf16 v[96:99], v[216:219], v[224:227], v[96:99]
	v_mfma_f32_16x16x32_bf16 v[104:107], v[220:223], v[224:227], v[104:107]
	ds_read_b128 v[224:227], v136 offset:8192
	s_waitcnt lgkmcnt(3)
	v_mfma_f32_16x16x32_bf16 v[116:119], v[180:183], v[228:231], v[116:119]
	v_mfma_f32_16x16x32_bf16 v[124:127], v[212:215], v[228:231], v[124:127]
	v_mfma_f32_16x16x32_bf16 v[100:103], v[216:219], v[228:231], v[100:103]
	v_mfma_f32_16x16x32_bf16 v[108:111], v[220:223], v[228:231], v[108:111]
	ds_read_b128 v[228:231], v136 offset:10240
	s_waitcnt lgkmcnt(3)
	v_mfma_f32_16x16x32_bf16 v[80:83], v[180:183], v[232:235], v[80:83]
	v_mfma_f32_16x16x32_bf16 v[88:91], v[212:215], v[232:235], v[88:91]
	v_mfma_f32_16x16x32_bf16 v[64:67], v[216:219], v[232:235], v[64:67]
	v_mfma_f32_16x16x32_bf16 v[72:75], v[220:223], v[232:235], v[72:75]
	ds_read_b128 v[232:235], v136 offset:12288
	s_waitcnt lgkmcnt(3)
	v_mfma_f32_16x16x32_bf16 v[84:87], v[180:183], v[236:239], v[84:87]
	v_mfma_f32_16x16x32_bf16 v[92:95], v[212:215], v[236:239], v[92:95]
	v_mfma_f32_16x16x32_bf16 v[68:71], v[216:219], v[236:239], v[68:71]
	v_mfma_f32_16x16x32_bf16 v[76:79], v[220:223], v[236:239], v[76:79]
	ds_read_b128 v[236:239], v136 offset:14336
	s_waitcnt lgkmcnt(3)
	v_mfma_f32_16x16x32_bf16 v[48:51], v[180:183], v[224:227], v[48:51]
	v_mfma_f32_16x16x32_bf16 v[56:59], v[212:215], v[224:227], v[56:59]
	v_mfma_f32_16x16x32_bf16 v[32:35], v[216:219], v[224:227], v[32:35]
	v_mfma_f32_16x16x32_bf16 v[40:43], v[220:223], v[224:227], v[40:43]
	s_waitcnt lgkmcnt(2)
	v_mfma_f32_16x16x32_bf16 v[52:55], v[180:183], v[228:231], v[52:55]
	v_mfma_f32_16x16x32_bf16 v[60:63], v[212:215], v[228:231], v[60:63]
	v_mfma_f32_16x16x32_bf16 v[36:39], v[216:219], v[228:231], v[36:39]
	v_mfma_f32_16x16x32_bf16 v[44:47], v[220:223], v[228:231], v[44:47]
	s_add_u32 m0, s52, s48
	s_nop 0
	global_load_lds_dwordx4 v138, s[56:57]
	s_add_u32 s56, s56, 0x80
	s_addc_u32 s57, s57, 0
	s_add_u32 s53, s52, s48
	s_add_u32 m0, s53, 0x2000
	s_nop 0
	global_load_lds_dwordx4 v138, s[58:59]
	s_add_u32 s58, s58, 0x80
	s_addc_u32 s59, s59, 0
	s_waitcnt lgkmcnt(1)
	v_mfma_f32_16x16x32_bf16 v[16:19], v[180:183], v[232:235], v[16:19]
	v_mfma_f32_16x16x32_bf16 v[24:27], v[212:215], v[232:235], v[24:27]
	v_mfma_f32_16x16x32_bf16 v[0:3], v[216:219], v[232:235], v[0:3]
	v_mfma_f32_16x16x32_bf16 v[8:11], v[220:223], v[232:235], v[8:11]
	s_add_u32 s53, s52, s48
	s_add_u32 m0, s53, 0x4000
	s_nop 0
	global_load_lds_dwordx4 v138, s[60:61]
	s_add_u32 s60, s60, 0x80
	s_addc_u32 s61, s61, 0
	s_add_u32 s53, s52, s48
	s_add_u32 m0, s53, 0x6000
	s_nop 0
	global_load_lds_dwordx4 v138, s[62:63]
	s_add_u32 s62, s62, 0x80
	s_addc_u32 s63, s63, 0
	s_waitcnt lgkmcnt(0)
	s_add_u32 s4, s4, 0x80
	s_addc_u32 s5, s5, 0
	s_add_u32 s49, s49, 0x10000
	s_sub_u32 s53, s49, 0x28000
	s_cmp_ge_u32 s49, 0x28000
	s_cselect_b32 s49, s53, s49
	s_mov_b32 s50, s51
	s_waitcnt vmcnt(4)
	s_barrier
	v_add_u32_e32 v137, s50, v134
	v_add_u32_e32 v136, s49, v132
	ds_read_b128 v[164:167], v137
	ds_read_b128 v[168:171], v137 offset:2048
	ds_read_b128 v[172:175], v137 offset:4096
	ds_read_b128 v[176:179], v137 offset:6144
	ds_read_b128 v[224:227], v136
	ds_read_b128 v[228:231], v136 offset:2048
	ds_read_b128 v[232:235], v136 offset:4096
	v_mfma_f32_16x16x32_bf16 v[20:23], v[180:183], v[236:239], v[20:23]
	v_mfma_f32_16x16x32_bf16 v[28:31], v[212:215], v[236:239], v[28:31]
	v_mfma_f32_16x16x32_bf16 v[4:7], v[216:219], v[236:239], v[4:7]
	v_mfma_f32_16x16x32_bf16 v[12:15], v[220:223], v[236:239], v[12:15]
	ds_read_b128 v[236:239], v136 offset:6144
	s_cmpk_lg_i32 s4, 0xf00
	s_cbranch_scc1 .Lg161_loop
	s_add_u32 s51, s50, 0x10000
	s_sub_u32 s53, s51, 0x28000
	s_cmp_ge_u32 s51, 0x28000
	s_cselect_b32 s51, s53, s51
	v_add_u32_e32 v137, s50, v135
	s_waitcnt lgkmcnt(4)
	s_waitcnt lgkmcnt(3)
	v_mfma_f32_16x16x32_bf16 v[112:115], v[164:167], v[224:227], v[112:115]
	v_mfma_f32_16x16x32_bf16 v[120:123], v[168:171], v[224:227], v[120:123]
	v_mfma_f32_16x16x32_bf16 v[96:99], v[172:175], v[224:227], v[96:99]
	v_mfma_f32_16x16x32_bf16 v[104:107], v[176:179], v[224:227], v[104:107]
	s_add_u32 m0, s51, s48
	s_nop 0
	global_load_lds_dwordx4 v139, s[64:65]
	s_add_u32 s64, s64, 0x80
	s_addc_u32 s65, s65, 0
	s_add_u32 s53, s51, s48
	s_add_u32 m0, s53, 0x2000
	s_nop 0
	global_load_lds_dwordx4 v139, s[66:67]
	s_add_u32 s66, s66, 0x80
	s_addc_u32 s67, s67, 0
	ds_read_b128 v[224:227], v136 offset:8192
	ds_read_b128 v[180:183], v137
	s_waitcnt lgkmcnt(4)
	v_mfma_f32_16x16x32_bf16 v[116:119], v[164:167], v[228:231], v[116:119]
	v_mfma_f32_16x16x32_bf16 v[124:127], v[168:171], v[228:231], v[124:127]
	v_mfma_f32_16x16x32_bf16 v[100:103], v[172:175], v[228:231], v[100:103]
	v_mfma_f32_16x16x32_bf16 v[108:111], v[176:179], v[228:231], v[108:111]
	s_add_u32 s53, s51, s48
	s_add_u32 m0, s53, 0x4000
	s_nop 0
	global_load_lds_dwordx4 v139, s[68:69]
	s_add_u32 s68, s68, 0x80
	s_addc_u32 s69, s69, 0
	s_add_u32 s53, s51, s48
	s_add_u32 m0, s53, 0x6000
	s_nop 0
	global_load_lds_dwordx4 v139, s[70:71]
	s_add_u32 s70, s70, 0x80
	s_addc_u32 s71, s71, 0
	ds_read_b128 v[228:231], v136 offset:10240
	ds_read_b128 v[212:215], v137 offset:2048
	s_waitcnt lgkmcnt(5)
	v_mfma_f32_16x16x32_bf16 v[80:83], v[164:167], v[232:235], v[80:83]
	v_mfma_f32_16x16x32_bf16 v[88:91], v[168:171], v[232:235], v[88:91]
	v_mfma_f32_16x16x32_bf16 v[64:67], v[172:175], v[232:235], v[64:67]
	v_mfma_f32_16x16x32_bf16 v[72:75], v[176:179], v[232:235], v[72:75]
	ds_read_b128 v[232:235], v136 offset:12288
	ds_read_b128 v[216:219], v137 offset:4096
	s_waitcnt lgkmcnt(6)
	v_mfma_f32_16x16x32_bf16 v[84:87], v[164:167], v[236:239], v[84:87]
	v_mfma_f32_16x16x32_bf16 v[92:95], v[168:171], v[236:239], v[92:95]
	v_mfma_f32_16x16x32_bf16 v[68:71], v[172:175], v[236:239], v[68:71]
	v_mfma_f32_16x16x32_bf16 v[76:79], v[176:179], v[236:239], v[76:79]
	ds_read_b128 v[236:239], v136 offset:14336
	ds_read_b128 v[220:223], v137 offset:6144
	v_add_u32_e32 v136, s49, v133
	s_waitcnt lgkmcnt(7)
	v_mfma_f32_16x16x32_bf16 v[48:51], v[164:167], v[224:227], v[48:51]
	v_mfma_f32_16x16x32_bf16 v[56:59], v[168:171], v[224:227], v[56:59]
	v_mfma_f32_16x16x32_bf16 v[32:35], v[172:175], v[224:227], v[32:35]
	v_mfma_f32_16x16x32_bf16 v[40:43], v[176:179], v[224:227], v[40:43]
	ds_read_b128 v[224:227], v136
	s_waitcnt lgkmcnt(6)
	v_mfma_f32_16x16x32_bf16 v[52:55], v[164:167], v[228:231], v[52:55]
	v_mfma_f32_16x16x32_bf16 v[60:63], v[168:171], v[228:231], v[60:63]
	v_mfma_f32_16x16x32_bf16 v[36:39], v[172:175], v[228:231], v[36:39]
	v_mfma_f32_16x16x32_bf16 v[44:47], v[176:179], v[228:231], v[44:47]
	ds_read_b128 v[228:231], v136 offset:2048
	s_waitcnt lgkmcnt(5)
	v_mfma_f32_16x16x32_bf16 v[16:19], v[164:167], v[232:235], v[16:19]
	v_mfma_f32_16x16x32_bf16 v[24:27], v[168:171], v[232:235], v[24:27]
	v_mfma_f32_16x16x32_bf16 v[0:3], v[172:175], v[232:235], v[0:3]
	v_mfma_f32_16x16x32_bf16 v[8:11], v[176:179], v[232:235], v[8:11]
	ds_read_b128 v[232:235], v136 offset:4096
	s_waitcnt lgkmcnt(4)
	v_mfma_f32_16x16x32_bf16 v[20:23], v[164:167], v[236:239], v[20:23]
	v_mfma_f32_16x16x32_bf16 v[28:31], v[168:171], v[236:239], v[28:31]
	v_mfma_f32_16x16x32_bf16 v[4:7], v[172:175], v[236:239], v[4:7]
	v_mfma_f32_16x16x32_bf16 v[12:15], v[176:179], v[236:239], v[12:15]
	ds_read_b128 v[236:239], v136 offset:6144
	s_waitcnt lgkmcnt(4)
	s_waitcnt lgkmcnt(3)
	v_mfma_f32_16x16x32_bf16 v[112:115], v[180:183], v[224:227], v[112:115]
	v_mfma_f32_16x16x32_bf16 v[120:123], v[212:215], v[224:227], v[120:123]
	v_mfma_f32_16x16x32_bf16 v[96:99], v[216:219], v[224:227], v[96:99]
	v_mfma_f32_16x16x32_bf16 v[104:107], v[220:223], v[224:227], v[104:107]
	ds_read_b128 v[224:227], v136 offset:8192
	s_waitcnt lgkmcnt(3)
	v_mfma_f32_16x16x32_bf16 v[116:119], v[180:183], v[228:231], v[116:119]
	v_mfma_f32_16x16x32_bf16 v[124:127], v[212:215], v[228:231], v[124:127]
	v_mfma_f32_16x16x32_bf16 v[100:103], v[216:219], v[228:231], v[100:103]
	v_mfma_f32_16x16x32_bf16 v[108:111], v[220:223], v[228:231], v[108:111]
	ds_read_b128 v[228:231], v136 offset:10240
	s_waitcnt lgkmcnt(3)
	v_mfma_f32_16x16x32_bf16 v[80:83], v[180:183], v[232:235], v[80:83]
	v_mfma_f32_16x16x32_bf16 v[88:91], v[212:215], v[232:235], v[88:91]
	v_mfma_f32_16x16x32_bf16 v[64:67], v[216:219], v[232:235], v[64:67]
	v_mfma_f32_16x16x32_bf16 v[72:75], v[220:223], v[232:235], v[72:75]
	ds_read_b128 v[232:235], v136 offset:12288
	s_waitcnt lgkmcnt(3)
	v_mfma_f32_16x16x32_bf16 v[84:87], v[180:183], v[236:239], v[84:87]
	v_mfma_f32_16x16x32_bf16 v[92:95], v[212:215], v[236:239], v[92:95]
	v_mfma_f32_16x16x32_bf16 v[68:71], v[216:219], v[236:239], v[68:71]
	v_mfma_f32_16x16x32_bf16 v[76:79], v[220:223], v[236:239], v[76:79]
	ds_read_b128 v[236:239], v136 offset:14336
	s_waitcnt lgkmcnt(3)
	v_mfma_f32_16x16x32_bf16 v[48:51], v[180:183], v[224:227], v[48:51]
	v_mfma_f32_16x16x32_bf16 v[56:59], v[212:215], v[224:227], v[56:59]
	v_mfma_f32_16x16x32_bf16 v[32:35], v[216:219], v[224:227], v[32:35]
	v_mfma_f32_16x16x32_bf16 v[40:43], v[220:223], v[224:227], v[40:43]
	s_waitcnt lgkmcnt(2)
	v_mfma_f32_16x16x32_bf16 v[52:55], v[180:183], v[228:231], v[52:55]
	v_mfma_f32_16x16x32_bf16 v[60:63], v[212:215], v[228:231], v[60:63]
	v_mfma_f32_16x16x32_bf16 v[36:39], v[216:219], v[228:231], v[36:39]
	v_mfma_f32_16x16x32_bf16 v[44:47], v[220:223], v[228:231], v[44:47]
	s_waitcnt lgkmcnt(1)
	v_mfma_f32_16x16x32_bf16 v[16:19], v[180:183], v[232:235], v[16:19]
	v_mfma_f32_16x16x32_bf16 v[24:27], v[212:215], v[232:235], v[24:27]
	v_mfma_f32_16x16x32_bf16 v[0:3], v[216:219], v[232:235], v[0:3]
	v_mfma_f32_16x16x32_bf16 v[8:11], v[220:223], v[232:235], v[8:11]
	s_waitcnt lgkmcnt(0)
	s_add_u32 s4, s4, 0x80
	s_addc_u32 s5, s5, 0
	s_add_u32 s49, s49, 0x10000
	s_sub_u32 s53, s49, 0x28000
	s_cmp_ge_u32 s49, 0x28000
	s_cselect_b32 s49, s53, s49
	s_mov_b32 s50, s51
	s_waitcnt vmcnt(0)
	s_barrier
	v_add_u32_e32 v137, s50, v134
	v_add_u32_e32 v136, s49, v132
	ds_read_b128 v[164:167], v137
	ds_read_b128 v[168:171], v137 offset:2048
	ds_read_b128 v[172:175], v137 offset:4096
	ds_read_b128 v[176:179], v137 offset:6144
	ds_read_b128 v[224:227], v136
	ds_read_b128 v[228:231], v136 offset:2048
	ds_read_b128 v[232:235], v136 offset:4096
	v_mfma_f32_16x16x32_bf16 v[20:23], v[180:183], v[236:239], v[20:23]
	v_mfma_f32_16x16x32_bf16 v[28:31], v[212:215], v[236:239], v[28:31]
	v_mfma_f32_16x16x32_bf16 v[4:7], v[216:219], v[236:239], v[4:7]
	v_mfma_f32_16x16x32_bf16 v[12:15], v[220:223], v[236:239], v[12:15]
	ds_read_b128 v[236:239], v136 offset:6144
	v_add_u32_e32 v137, s50, v135
	s_waitcnt lgkmcnt(4)
	s_waitcnt lgkmcnt(3)
	v_mfma_f32_16x16x32_bf16 v[112:115], v[164:167], v[224:227], v[112:115]
	v_mfma_f32_16x16x32_bf16 v[120:123], v[168:171], v[224:227], v[120:123]
	v_mfma_f32_16x16x32_bf16 v[96:99], v[172:175], v[224:227], v[96:99]
	v_mfma_f32_16x16x32_bf16 v[104:107], v[176:179], v[224:227], v[104:107]
	ds_read_b128 v[224:227], v136 offset:8192
	ds_read_b128 v[180:183], v137
	s_waitcnt lgkmcnt(4)
	v_mfma_f32_16x16x32_bf16 v[116:119], v[164:167], v[228:231], v[116:119]
	v_mfma_f32_16x16x32_bf16 v[124:127], v[168:171], v[228:231], v[124:127]
	v_mfma_f32_16x16x32_bf16 v[100:103], v[172:175], v[228:231], v[100:103]
	v_mfma_f32_16x16x32_bf16 v[108:111], v[176:179], v[228:231], v[108:111]
	ds_read_b128 v[228:231], v136 offset:10240
	ds_read_b128 v[212:215], v137 offset:2048
	s_waitcnt lgkmcnt(5)
	v_mfma_f32_16x16x32_bf16 v[80:83], v[164:167], v[232:235], v[80:83]
	v_mfma_f32_16x16x32_bf16 v[88:91], v[168:171], v[232:235], v[88:91]
	v_mfma_f32_16x16x32_bf16 v[64:67], v[172:175], v[232:235], v[64:67]
	v_mfma_f32_16x16x32_bf16 v[72:75], v[176:179], v[232:235], v[72:75]
	ds_read_b128 v[232:235], v136 offset:12288
	ds_read_b128 v[216:219], v137 offset:4096
	s_waitcnt lgkmcnt(6)
	v_mfma_f32_16x16x32_bf16 v[84:87], v[164:167], v[236:239], v[84:87]
	v_mfma_f32_16x16x32_bf16 v[92:95], v[168:171], v[236:239], v[92:95]
	v_mfma_f32_16x16x32_bf16 v[68:71], v[172:175], v[236:239], v[68:71]
	v_mfma_f32_16x16x32_bf16 v[76:79], v[176:179], v[236:239], v[76:79]
	ds_read_b128 v[236:239], v136 offset:14336
	ds_read_b128 v[220:223], v137 offset:6144
	v_add_u32_e32 v136, s49, v133
	s_waitcnt lgkmcnt(7)
	v_mfma_f32_16x16x32_bf16 v[48:51], v[164:167], v[224:227], v[48:51]
	v_mfma_f32_16x16x32_bf16 v[56:59], v[168:171], v[224:227], v[56:59]
	v_mfma_f32_16x16x32_bf16 v[32:35], v[172:175], v[224:227], v[32:35]
	v_mfma_f32_16x16x32_bf16 v[40:43], v[176:179], v[224:227], v[40:43]
	ds_read_b128 v[224:227], v136
	s_waitcnt lgkmcnt(6)
	v_mfma_f32_16x16x32_bf16 v[52:55], v[164:167], v[228:231], v[52:55]
	v_mfma_f32_16x16x32_bf16 v[60:63], v[168:171], v[228:231], v[60:63]
	v_mfma_f32_16x16x32_bf16 v[36:39], v[172:175], v[228:231], v[36:39]
	v_mfma_f32_16x16x32_bf16 v[44:47], v[176:179], v[228:231], v[44:47]
	ds_read_b128 v[228:231], v136 offset:2048
	s_waitcnt lgkmcnt(5)
	v_mfma_f32_16x16x32_bf16 v[16:19], v[164:167], v[232:235], v[16:19]
	v_mfma_f32_16x16x32_bf16 v[24:27], v[168:171], v[232:235], v[24:27]
	v_mfma_f32_16x16x32_bf16 v[0:3], v[172:175], v[232:235], v[0:3]
	v_mfma_f32_16x16x32_bf16 v[8:11], v[176:179], v[232:235], v[8:11]
	ds_read_b128 v[232:235], v136 offset:4096
	s_waitcnt lgkmcnt(4)
	v_mfma_f32_16x16x32_bf16 v[20:23], v[164:167], v[236:239], v[20:23]
	v_mfma_f32_16x16x32_bf16 v[28:31], v[168:171], v[236:239], v[28:31]
	v_mfma_f32_16x16x32_bf16 v[4:7], v[172:175], v[236:239], v[4:7]
	v_mfma_f32_16x16x32_bf16 v[12:15], v[176:179], v[236:239], v[12:15]
	ds_read_b128 v[236:239], v136 offset:6144
	s_waitcnt lgkmcnt(4)
	s_waitcnt lgkmcnt(3)
	v_mfma_f32_16x16x32_bf16 v[112:115], v[180:183], v[224:227], v[112:115]
	v_mfma_f32_16x16x32_bf16 v[120:123], v[212:215], v[224:227], v[120:123]
	v_mfma_f32_16x16x32_bf16 v[96:99], v[216:219], v[224:227], v[96:99]
	v_mfma_f32_16x16x32_bf16 v[104:107], v[220:223], v[224:227], v[104:107]
	ds_read_b128 v[224:227], v136 offset:8192
	s_waitcnt lgkmcnt(3)
	v_mfma_f32_16x16x32_bf16 v[116:119], v[180:183], v[228:231], v[116:119]
	v_mfma_f32_16x16x32_bf16 v[124:127], v[212:215], v[228:231], v[124:127]
	v_mfma_f32_16x16x32_bf16 v[100:103], v[216:219], v[228:231], v[100:103]
	v_mfma_f32_16x16x32_bf16 v[108:111], v[220:223], v[228:231], v[108:111]
	ds_read_b128 v[228:231], v136 offset:10240
	s_waitcnt lgkmcnt(3)
	v_mfma_f32_16x16x32_bf16 v[80:83], v[180:183], v[232:235], v[80:83]
	v_mfma_f32_16x16x32_bf16 v[88:91], v[212:215], v[232:235], v[88:91]
	v_mfma_f32_16x16x32_bf16 v[64:67], v[216:219], v[232:235], v[64:67]
	v_mfma_f32_16x16x32_bf16 v[72:75], v[220:223], v[232:235], v[72:75]
	ds_read_b128 v[232:235], v136 offset:12288
	s_waitcnt lgkmcnt(3)
	v_mfma_f32_16x16x32_bf16 v[84:87], v[180:183], v[236:239], v[84:87]
	v_mfma_f32_16x16x32_bf16 v[92:95], v[212:215], v[236:239], v[92:95]
	v_mfma_f32_16x16x32_bf16 v[68:71], v[216:219], v[236:239], v[68:71]
	v_mfma_f32_16x16x32_bf16 v[76:79], v[220:223], v[236:239], v[76:79]
	ds_read_b128 v[236:239], v136 offset:14336
	s_waitcnt lgkmcnt(3)
	v_mfma_f32_16x16x32_bf16 v[48:51], v[180:183], v[224:227], v[48:51]
	v_mfma_f32_16x16x32_bf16 v[56:59], v[212:215], v[224:227], v[56:59]
	v_mfma_f32_16x16x32_bf16 v[32:35], v[216:219], v[224:227], v[32:35]
	v_mfma_f32_16x16x32_bf16 v[40:43], v[220:223], v[224:227], v[40:43]
	s_waitcnt lgkmcnt(2)
	v_mfma_f32_16x16x32_bf16 v[52:55], v[180:183], v[228:231], v[52:55]
	v_mfma_f32_16x16x32_bf16 v[60:63], v[212:215], v[228:231], v[60:63]
	v_mfma_f32_16x16x32_bf16 v[36:39], v[216:219], v[228:231], v[36:39]
	v_mfma_f32_16x16x32_bf16 v[44:47], v[220:223], v[228:231], v[44:47]
	s_waitcnt lgkmcnt(1)
	v_mfma_f32_16x16x32_bf16 v[16:19], v[180:183], v[232:235], v[16:19]
	v_mfma_f32_16x16x32_bf16 v[24:27], v[212:215], v[232:235], v[24:27]
	v_mfma_f32_16x16x32_bf16 v[0:3], v[216:219], v[232:235], v[0:3]
	v_mfma_f32_16x16x32_bf16 v[8:11], v[220:223], v[232:235], v[8:11]
	s_waitcnt lgkmcnt(0)
	s_waitcnt vmcnt(0)
	s_barrier
	v_mfma_f32_16x16x32_bf16 v[20:23], v[180:183], v[236:239], v[20:23]
	v_mfma_f32_16x16x32_bf16 v[28:31], v[212:215], v[236:239], v[28:31]
	v_mfma_f32_16x16x32_bf16 v[4:7], v[216:219], v[236:239], v[4:7]
	v_mfma_f32_16x16x32_bf16 v[12:15], v[220:223], v[236:239], v[12:15]
	s_nop 15
	v_permlane16_swap_b32_e32 v112, v116
	v_permlane16_swap_b32_e32 v113, v117
	v_permlane16_swap_b32_e32 v114, v118
	v_permlane16_swap_b32_e32 v115, v119
	v_permlane16_swap_b32_e32 v120, v124
	v_permlane16_swap_b32_e32 v121, v125
	v_permlane16_swap_b32_e32 v122, v126
	v_permlane16_swap_b32_e32 v123, v127
	v_permlane16_swap_b32_e32 v96, v100
	v_permlane16_swap_b32_e32 v97, v101
	v_permlane16_swap_b32_e32 v98, v102
	v_permlane16_swap_b32_e32 v99, v103
	v_permlane16_swap_b32_e32 v104, v108
	v_permlane16_swap_b32_e32 v105, v109
	v_permlane16_swap_b32_e32 v106, v110
	v_permlane16_swap_b32_e32 v107, v111
	v_permlane16_swap_b32_e32 v80, v84
	v_permlane16_swap_b32_e32 v81, v85
	v_permlane16_swap_b32_e32 v82, v86
	v_permlane16_swap_b32_e32 v83, v87
	v_permlane16_swap_b32_e32 v88, v92
	v_permlane16_swap_b32_e32 v89, v93
	v_permlane16_swap_b32_e32 v90, v94
	v_permlane16_swap_b32_e32 v91, v95
	v_permlane16_swap_b32_e32 v64, v68
	v_permlane16_swap_b32_e32 v65, v69
	v_permlane16_swap_b32_e32 v66, v70
	v_permlane16_swap_b32_e32 v67, v71
	v_permlane16_swap_b32_e32 v72, v76
	v_permlane16_swap_b32_e32 v73, v77
	v_permlane16_swap_b32_e32 v74, v78
	v_permlane16_swap_b32_e32 v75, v79
	v_permlane16_swap_b32_e32 v48, v52
	v_permlane16_swap_b32_e32 v49, v53
	v_permlane16_swap_b32_e32 v50, v54
	v_permlane16_swap_b32_e32 v51, v55
	v_permlane16_swap_b32_e32 v56, v60
	v_permlane16_swap_b32_e32 v57, v61
	v_permlane16_swap_b32_e32 v58, v62
	v_permlane16_swap_b32_e32 v59, v63
	v_permlane16_swap_b32_e32 v32, v36
	v_permlane16_swap_b32_e32 v33, v37
	v_permlane16_swap_b32_e32 v34, v38
	v_permlane16_swap_b32_e32 v35, v39
	v_permlane16_swap_b32_e32 v40, v44
	v_permlane16_swap_b32_e32 v41, v45
	v_permlane16_swap_b32_e32 v42, v46
	v_permlane16_swap_b32_e32 v43, v47
	v_permlane16_swap_b32_e32 v16, v20
	v_permlane16_swap_b32_e32 v17, v21
	v_permlane16_swap_b32_e32 v18, v22
	v_permlane16_swap_b32_e32 v19, v23
	v_permlane16_swap_b32_e32 v24, v28
	v_permlane16_swap_b32_e32 v25, v29
	v_permlane16_swap_b32_e32 v26, v30
	v_permlane16_swap_b32_e32 v27, v31
	v_permlane16_swap_b32_e32 v0, v4
	v_permlane16_swap_b32_e32 v1, v5
	v_permlane16_swap_b32_e32 v2, v6
	v_permlane16_swap_b32_e32 v3, v7
	v_permlane16_swap_b32_e32 v8, v12
	v_permlane16_swap_b32_e32 v9, v13
	v_permlane16_swap_b32_e32 v10, v14
	v_permlane16_swap_b32_e32 v11, v15
	v_permlane32_swap_b32_e32 v112, v116
	v_permlane32_swap_b32_e32 v113, v117
	v_permlane32_swap_b32_e32 v114, v118
	v_permlane32_swap_b32_e32 v115, v119
	v_permlane32_swap_b32_e32 v120, v124
	v_permlane32_swap_b32_e32 v121, v125
	v_permlane32_swap_b32_e32 v122, v126
	v_permlane32_swap_b32_e32 v123, v127
	v_permlane32_swap_b32_e32 v96, v100
	v_permlane32_swap_b32_e32 v97, v101
	v_permlane32_swap_b32_e32 v98, v102
	v_permlane32_swap_b32_e32 v99, v103
	v_permlane32_swap_b32_e32 v104, v108
	v_permlane32_swap_b32_e32 v105, v109
	v_permlane32_swap_b32_e32 v106, v110
	v_permlane32_swap_b32_e32 v107, v111
	v_permlane32_swap_b32_e32 v80, v84
	v_permlane32_swap_b32_e32 v81, v85
	v_permlane32_swap_b32_e32 v82, v86
	v_permlane32_swap_b32_e32 v83, v87
	v_permlane32_swap_b32_e32 v88, v92
	v_permlane32_swap_b32_e32 v89, v93
	v_permlane32_swap_b32_e32 v90, v94
	v_permlane32_swap_b32_e32 v91, v95
	v_permlane32_swap_b32_e32 v64, v68
	v_permlane32_swap_b32_e32 v65, v69
	v_permlane32_swap_b32_e32 v66, v70
	v_permlane32_swap_b32_e32 v67, v71
	v_permlane32_swap_b32_e32 v72, v76
	v_permlane32_swap_b32_e32 v73, v77
	v_permlane32_swap_b32_e32 v74, v78
	v_permlane32_swap_b32_e32 v75, v79
	v_permlane32_swap_b32_e32 v48, v52
	v_permlane32_swap_b32_e32 v49, v53
	v_permlane32_swap_b32_e32 v50, v54
	v_permlane32_swap_b32_e32 v51, v55
	v_permlane32_swap_b32_e32 v56, v60
	v_permlane32_swap_b32_e32 v57, v61
	v_permlane32_swap_b32_e32 v58, v62
	v_permlane32_swap_b32_e32 v59, v63
	v_permlane32_swap_b32_e32 v32, v36
	v_permlane32_swap_b32_e32 v33, v37
	v_permlane32_swap_b32_e32 v34, v38
	v_permlane32_swap_b32_e32 v35, v39
	v_permlane32_swap_b32_e32 v40, v44
	v_permlane32_swap_b32_e32 v41, v45
	v_permlane32_swap_b32_e32 v42, v46
	v_permlane32_swap_b32_e32 v43, v47
	v_permlane32_swap_b32_e32 v16, v20
	v_permlane32_swap_b32_e32 v17, v21
	v_permlane32_swap_b32_e32 v18, v22
	v_permlane32_swap_b32_e32 v19, v23
	v_permlane32_swap_b32_e32 v24, v28
	v_permlane32_swap_b32_e32 v25, v29
	v_permlane32_swap_b32_e32 v26, v30
	v_permlane32_swap_b32_e32 v27, v31
	v_permlane32_swap_b32_e32 v0, v4
	v_permlane32_swap_b32_e32 v1, v5
	v_permlane32_swap_b32_e32 v2, v6
	v_permlane32_swap_b32_e32 v3, v7
	v_permlane32_swap_b32_e32 v8, v12
	v_permlane32_swap_b32_e32 v9, v13
	v_permlane32_swap_b32_e32 v10, v14
	v_permlane32_swap_b32_e32 v11, v15
	s_nop 1

.Lg162_loop:
	s_add_u32 s51, s50, 0x10000
	s_sub_u32 s53, s51, 0x28000
	s_cmp_ge_u32 s51, 0x28000
	s_cselect_b32 s51, s53, s51
	s_add_u32 s52, s49, 0x20000
	s_sub_u32 s53, s52, 0x28000
	s_cmp_ge_u32 s52, 0x28000
	s_cselect_b32 s52, s53, s52
	v_add_u32_e32 v167, s50, v145
	s_waitcnt lgkmcnt(4)
	s_waitcnt lgkmcnt(3)
	v_mfma_f32_16x16x32_bf16 v[112:115], v[188:191], v[220:223], v[112:115]
	v_mfma_f32_16x16x32_bf16 v[120:123], v[192:195], v[220:223], v[120:123]
	v_mfma_f32_16x16x32_bf16 v[96:99], v[196:199], v[220:223], v[96:99]
	v_mfma_f32_16x16x32_bf16 v[104:107], v[200:203], v[220:223], v[104:107]
	s_add_u32 m0, s51, s48
	s_nop 0
	global_load_lds_dwordx4 v169, s[64:65]
	s_add_u32 s64, s64, 0x80
	s_addc_u32 s65, s65, 0
	s_add_u32 s53, s51, s48
	s_add_u32 m0, s53, 0x2000
	s_nop 0
	global_load_lds_dwordx4 v169, s[66:67]
	s_add_u32 s66, s66, 0x80
	s_addc_u32 s67, s67, 0
	ds_read_b128 v[220:223], v166 offset:8192
	ds_read_b128 v[204:207], v167
	s_waitcnt lgkmcnt(4)
	v_mfma_f32_16x16x32_bf16 v[116:119], v[188:191], v[224:227], v[116:119]
	v_mfma_f32_16x16x32_bf16 v[124:127], v[192:195], v[224:227], v[124:127]
	v_mfma_f32_16x16x32_bf16 v[100:103], v[196:199], v[224:227], v[100:103]
	v_mfma_f32_16x16x32_bf16 v[108:111], v[200:203], v[224:227], v[108:111]
	s_add_u32 s53, s51, s48
	s_add_u32 m0, s53, 0x4000
	s_nop 0
	global_load_lds_dwordx4 v169, s[68:69]
	s_add_u32 s68, s68, 0x80
	s_addc_u32 s69, s69, 0
	s_add_u32 s53, s51, s48
	s_add_u32 m0, s53, 0x6000
	s_nop 0
	global_load_lds_dwordx4 v169, s[70:71]
	s_add_u32 s70, s70, 0x80
	s_addc_u32 s71, s71, 0
	ds_read_b128 v[224:227], v166 offset:10240
	ds_read_b128 v[208:211], v167 offset:2048
	s_waitcnt lgkmcnt(5)
	v_mfma_f32_16x16x32_bf16 v[80:83], v[188:191], v[228:231], v[80:83]
	v_mfma_f32_16x16x32_bf16 v[88:91], v[192:195], v[228:231], v[88:91]
	v_mfma_f32_16x16x32_bf16 v[64:67], v[196:199], v[228:231], v[64:67]
	v_mfma_f32_16x16x32_bf16 v[72:75], v[200:203], v[228:231], v[72:75]
	ds_read_b128 v[228:231], v166 offset:12288
	ds_read_b128 v[212:215], v167 offset:4096
	s_waitcnt lgkmcnt(6)
	v_mfma_f32_16x16x32_bf16 v[84:87], v[188:191], v[232:235], v[84:87]
	v_mfma_f32_16x16x32_bf16 v[92:95], v[192:195], v[232:235], v[92:95]
	v_mfma_f32_16x16x32_bf16 v[68:71], v[196:199], v[232:235], v[68:71]
	v_mfma_f32_16x16x32_bf16 v[76:79], v[200:203], v[232:235], v[76:79]
	ds_read_b128 v[232:235], v166 offset:14336
	ds_read_b128 v[216:219], v167 offset:6144
	v_add_u32_e32 v166, s49, v143
	s_waitcnt lgkmcnt(7)
	v_mfma_f32_16x16x32_bf16 v[48:51], v[188:191], v[220:223], v[48:51]
	v_mfma_f32_16x16x32_bf16 v[56:59], v[192:195], v[220:223], v[56:59]
	v_mfma_f32_16x16x32_bf16 v[32:35], v[196:199], v[220:223], v[32:35]
	v_mfma_f32_16x16x32_bf16 v[40:43], v[200:203], v[220:223], v[40:43]
	ds_read_b128 v[220:223], v166
	s_waitcnt lgkmcnt(6)
	v_mfma_f32_16x16x32_bf16 v[52:55], v[188:191], v[224:227], v[52:55]
	v_mfma_f32_16x16x32_bf16 v[60:63], v[192:195], v[224:227], v[60:63]
	v_mfma_f32_16x16x32_bf16 v[36:39], v[196:199], v[224:227], v[36:39]
	v_mfma_f32_16x16x32_bf16 v[44:47], v[200:203], v[224:227], v[44:47]
	ds_read_b128 v[224:227], v166 offset:2048
	s_waitcnt lgkmcnt(5)
	v_mfma_f32_16x16x32_bf16 v[16:19], v[188:191], v[228:231], v[16:19]
	v_mfma_f32_16x16x32_bf16 v[24:27], v[192:195], v[228:231], v[24:27]
	v_mfma_f32_16x16x32_bf16 v[0:3], v[196:199], v[228:231], v[0:3]
	v_mfma_f32_16x16x32_bf16 v[8:11], v[200:203], v[228:231], v[8:11]
	ds_read_b128 v[228:231], v166 offset:4096
	s_waitcnt lgkmcnt(4)
	v_mfma_f32_16x16x32_bf16 v[20:23], v[188:191], v[232:235], v[20:23]
	v_mfma_f32_16x16x32_bf16 v[28:31], v[192:195], v[232:235], v[28:31]
	v_mfma_f32_16x16x32_bf16 v[4:7], v[196:199], v[232:235], v[4:7]
	v_mfma_f32_16x16x32_bf16 v[12:15], v[200:203], v[232:235], v[12:15]
	ds_read_b128 v[232:235], v166 offset:6144
	s_waitcnt lgkmcnt(4)
	s_waitcnt lgkmcnt(3)
	v_mfma_f32_16x16x32_bf16 v[112:115], v[204:207], v[220:223], v[112:115]
	v_mfma_f32_16x16x32_bf16 v[120:123], v[208:211], v[220:223], v[120:123]
	v_mfma_f32_16x16x32_bf16 v[96:99], v[212:215], v[220:223], v[96:99]
	v_mfma_f32_16x16x32_bf16 v[104:107], v[216:219], v[220:223], v[104:107]
	ds_read_b128 v[220:223], v166 offset:8192
	s_waitcnt lgkmcnt(3)
	v_mfma_f32_16x16x32_bf16 v[116:119], v[204:207], v[224:227], v[116:119]
	v_mfma_f32_16x16x32_bf16 v[124:127], v[208:211], v[224:227], v[124:127]
	v_mfma_f32_16x16x32_bf16 v[100:103], v[212:215], v[224:227], v[100:103]
	v_mfma_f32_16x16x32_bf16 v[108:111], v[216:219], v[224:227], v[108:111]
	ds_read_b128 v[224:227], v166 offset:10240
	s_waitcnt lgkmcnt(3)
	v_mfma_f32_16x16x32_bf16 v[80:83], v[204:207], v[228:231], v[80:83]
	v_mfma_f32_16x16x32_bf16 v[88:91], v[208:211], v[228:231], v[88:91]
	v_mfma_f32_16x16x32_bf16 v[64:67], v[212:215], v[228:231], v[64:67]
	v_mfma_f32_16x16x32_bf16 v[72:75], v[216:219], v[228:231], v[72:75]
	ds_read_b128 v[228:231], v166 offset:12288
	s_waitcnt lgkmcnt(3)
	v_mfma_f32_16x16x32_bf16 v[84:87], v[204:207], v[232:235], v[84:87]
	v_mfma_f32_16x16x32_bf16 v[92:95], v[208:211], v[232:235], v[92:95]
	v_mfma_f32_16x16x32_bf16 v[68:71], v[212:215], v[232:235], v[68:71]
	v_mfma_f32_16x16x32_bf16 v[76:79], v[216:219], v[232:235], v[76:79]
	ds_read_b128 v[232:235], v166 offset:14336
	s_waitcnt lgkmcnt(3)
	v_mfma_f32_16x16x32_bf16 v[48:51], v[204:207], v[220:223], v[48:51]
	v_mfma_f32_16x16x32_bf16 v[56:59], v[208:211], v[220:223], v[56:59]
	v_mfma_f32_16x16x32_bf16 v[32:35], v[212:215], v[220:223], v[32:35]
	v_mfma_f32_16x16x32_bf16 v[40:43], v[216:219], v[220:223], v[40:43]
	s_waitcnt lgkmcnt(2)
	v_mfma_f32_16x16x32_bf16 v[52:55], v[204:207], v[224:227], v[52:55]
	v_mfma_f32_16x16x32_bf16 v[60:63], v[208:211], v[224:227], v[60:63]
	v_mfma_f32_16x16x32_bf16 v[36:39], v[212:215], v[224:227], v[36:39]
	v_mfma_f32_16x16x32_bf16 v[44:47], v[216:219], v[224:227], v[44:47]
	s_add_u32 m0, s52, s48
	s_nop 0
	global_load_lds_dwordx4 v168, s[56:57]
	s_add_u32 s56, s56, 0x80
	s_addc_u32 s57, s57, 0
	s_add_u32 s53, s52, s48
	s_add_u32 m0, s53, 0x2000
	s_nop 0
	global_load_lds_dwordx4 v168, s[58:59]
	s_add_u32 s58, s58, 0x80
	s_addc_u32 s59, s59, 0
	s_waitcnt lgkmcnt(1)
	v_mfma_f32_16x16x32_bf16 v[16:19], v[204:207], v[228:231], v[16:19]
	v_mfma_f32_16x16x32_bf16 v[24:27], v[208:211], v[228:231], v[24:27]
	v_mfma_f32_16x16x32_bf16 v[0:3], v[212:215], v[228:231], v[0:3]
	v_mfma_f32_16x16x32_bf16 v[8:11], v[216:219], v[228:231], v[8:11]
	s_add_u32 s53, s52, s48
	s_add_u32 m0, s53, 0x4000
	s_nop 0
	global_load_lds_dwordx4 v168, s[60:61]
	s_add_u32 s60, s60, 0x80
	s_addc_u32 s61, s61, 0
	s_add_u32 s53, s52, s48
	s_add_u32 m0, s53, 0x6000
	s_nop 0
	global_load_lds_dwordx4 v168, s[62:63]
	s_add_u32 s62, s62, 0x80
	s_addc_u32 s63, s63, 0
	s_waitcnt lgkmcnt(0)
	s_add_u32 s28, s28, 0x80
	s_addc_u32 s29, s29, 0
	s_add_u32 s49, s49, 0x10000
	s_sub_u32 s53, s49, 0x28000
	s_cmp_ge_u32 s49, 0x28000
	s_cselect_b32 s49, s53, s49
	s_mov_b32 s50, s51
	s_waitcnt vmcnt(4)
	s_barrier
	v_add_u32_e32 v167, s50, v144
	v_add_u32_e32 v166, s49, v142
	ds_read_b128 v[188:191], v167
	ds_read_b128 v[192:195], v167 offset:2048
	ds_read_b128 v[196:199], v167 offset:4096
	ds_read_b128 v[200:203], v167 offset:6144
	ds_read_b128 v[220:223], v166
	ds_read_b128 v[224:227], v166 offset:2048
	ds_read_b128 v[228:231], v166 offset:4096
	v_mfma_f32_16x16x32_bf16 v[20:23], v[204:207], v[232:235], v[20:23]
	v_mfma_f32_16x16x32_bf16 v[28:31], v[208:211], v[232:235], v[28:31]
	v_mfma_f32_16x16x32_bf16 v[4:7], v[212:215], v[232:235], v[4:7]
	v_mfma_f32_16x16x32_bf16 v[12:15], v[216:219], v[232:235], v[12:15]
	ds_read_b128 v[232:235], v166 offset:6144
	s_cmpk_lg_i32 s28, 0xf00
	s_cbranch_scc1 .Lg162_loop
	s_add_u32 s51, s50, 0x10000
	s_sub_u32 s53, s51, 0x28000
	s_cmp_ge_u32 s51, 0x28000
	s_cselect_b32 s51, s53, s51
	v_add_u32_e32 v167, s50, v145
	s_waitcnt lgkmcnt(4)
	s_waitcnt lgkmcnt(3)
	v_mfma_f32_16x16x32_bf16 v[112:115], v[188:191], v[220:223], v[112:115]
	v_mfma_f32_16x16x32_bf16 v[120:123], v[192:195], v[220:223], v[120:123]
	v_mfma_f32_16x16x32_bf16 v[96:99], v[196:199], v[220:223], v[96:99]
	v_mfma_f32_16x16x32_bf16 v[104:107], v[200:203], v[220:223], v[104:107]
	s_add_u32 m0, s51, s48
	s_nop 0
	global_load_lds_dwordx4 v169, s[64:65]
	s_add_u32 s64, s64, 0x80
	s_addc_u32 s65, s65, 0
	s_add_u32 s53, s51, s48
	s_add_u32 m0, s53, 0x2000
	s_nop 0
	global_load_lds_dwordx4 v169, s[66:67]
	s_add_u32 s66, s66, 0x80
	s_addc_u32 s67, s67, 0
	ds_read_b128 v[220:223], v166 offset:8192
	ds_read_b128 v[204:207], v167
	s_waitcnt lgkmcnt(4)
	v_mfma_f32_16x16x32_bf16 v[116:119], v[188:191], v[224:227], v[116:119]
	v_mfma_f32_16x16x32_bf16 v[124:127], v[192:195], v[224:227], v[124:127]
	v_mfma_f32_16x16x32_bf16 v[100:103], v[196:199], v[224:227], v[100:103]
	v_mfma_f32_16x16x32_bf16 v[108:111], v[200:203], v[224:227], v[108:111]
	s_add_u32 s53, s51, s48
	s_add_u32 m0, s53, 0x4000
	s_nop 0
	global_load_lds_dwordx4 v169, s[68:69]
	s_add_u32 s68, s68, 0x80
	s_addc_u32 s69, s69, 0
	s_add_u32 s53, s51, s48
	s_add_u32 m0, s53, 0x6000
	s_nop 0
	global_load_lds_dwordx4 v169, s[70:71]
	s_add_u32 s70, s70, 0x80
	s_addc_u32 s71, s71, 0
	ds_read_b128 v[224:227], v166 offset:10240
	ds_read_b128 v[208:211], v167 offset:2048
	s_waitcnt lgkmcnt(5)
	v_mfma_f32_16x16x32_bf16 v[80:83], v[188:191], v[228:231], v[80:83]
	v_mfma_f32_16x16x32_bf16 v[88:91], v[192:195], v[228:231], v[88:91]
	v_mfma_f32_16x16x32_bf16 v[64:67], v[196:199], v[228:231], v[64:67]
	v_mfma_f32_16x16x32_bf16 v[72:75], v[200:203], v[228:231], v[72:75]
	ds_read_b128 v[228:231], v166 offset:12288
	ds_read_b128 v[212:215], v167 offset:4096
	s_waitcnt lgkmcnt(6)
	v_mfma_f32_16x16x32_bf16 v[84:87], v[188:191], v[232:235], v[84:87]
	v_mfma_f32_16x16x32_bf16 v[92:95], v[192:195], v[232:235], v[92:95]
	v_mfma_f32_16x16x32_bf16 v[68:71], v[196:199], v[232:235], v[68:71]
	v_mfma_f32_16x16x32_bf16 v[76:79], v[200:203], v[232:235], v[76:79]
	ds_read_b128 v[232:235], v166 offset:14336
	ds_read_b128 v[216:219], v167 offset:6144
	v_add_u32_e32 v166, s49, v143
	s_waitcnt lgkmcnt(7)
	v_mfma_f32_16x16x32_bf16 v[48:51], v[188:191], v[220:223], v[48:51]
	v_mfma_f32_16x16x32_bf16 v[56:59], v[192:195], v[220:223], v[56:59]
	v_mfma_f32_16x16x32_bf16 v[32:35], v[196:199], v[220:223], v[32:35]
	v_mfma_f32_16x16x32_bf16 v[40:43], v[200:203], v[220:223], v[40:43]
	ds_read_b128 v[220:223], v166
	s_waitcnt lgkmcnt(6)
	v_mfma_f32_16x16x32_bf16 v[52:55], v[188:191], v[224:227], v[52:55]
	v_mfma_f32_16x16x32_bf16 v[60:63], v[192:195], v[224:227], v[60:63]
	v_mfma_f32_16x16x32_bf16 v[36:39], v[196:199], v[224:227], v[36:39]
	v_mfma_f32_16x16x32_bf16 v[44:47], v[200:203], v[224:227], v[44:47]
	ds_read_b128 v[224:227], v166 offset:2048
	s_waitcnt lgkmcnt(5)
	v_mfma_f32_16x16x32_bf16 v[16:19], v[188:191], v[228:231], v[16:19]
	v_mfma_f32_16x16x32_bf16 v[24:27], v[192:195], v[228:231], v[24:27]
	v_mfma_f32_16x16x32_bf16 v[0:3], v[196:199], v[228:231], v[0:3]
	v_mfma_f32_16x16x32_bf16 v[8:11], v[200:203], v[228:231], v[8:11]
	ds_read_b128 v[228:231], v166 offset:4096
	s_waitcnt lgkmcnt(4)
	v_mfma_f32_16x16x32_bf16 v[20:23], v[188:191], v[232:235], v[20:23]
	v_mfma_f32_16x16x32_bf16 v[28:31], v[192:195], v[232:235], v[28:31]
	v_mfma_f32_16x16x32_bf16 v[4:7], v[196:199], v[232:235], v[4:7]
	v_mfma_f32_16x16x32_bf16 v[12:15], v[200:203], v[232:235], v[12:15]
	ds_read_b128 v[232:235], v166 offset:6144
	s_waitcnt lgkmcnt(4)
	s_waitcnt lgkmcnt(3)
	v_mfma_f32_16x16x32_bf16 v[112:115], v[204:207], v[220:223], v[112:115]
	v_mfma_f32_16x16x32_bf16 v[120:123], v[208:211], v[220:223], v[120:123]
	v_mfma_f32_16x16x32_bf16 v[96:99], v[212:215], v[220:223], v[96:99]
	v_mfma_f32_16x16x32_bf16 v[104:107], v[216:219], v[220:223], v[104:107]
	ds_read_b128 v[220:223], v166 offset:8192
	s_waitcnt lgkmcnt(3)
	v_mfma_f32_16x16x32_bf16 v[116:119], v[204:207], v[224:227], v[116:119]
	v_mfma_f32_16x16x32_bf16 v[124:127], v[208:211], v[224:227], v[124:127]
	v_mfma_f32_16x16x32_bf16 v[100:103], v[212:215], v[224:227], v[100:103]
	v_mfma_f32_16x16x32_bf16 v[108:111], v[216:219], v[224:227], v[108:111]
	ds_read_b128 v[224:227], v166 offset:10240
	s_waitcnt lgkmcnt(3)
	v_mfma_f32_16x16x32_bf16 v[80:83], v[204:207], v[228:231], v[80:83]
	v_mfma_f32_16x16x32_bf16 v[88:91], v[208:211], v[228:231], v[88:91]
	v_mfma_f32_16x16x32_bf16 v[64:67], v[212:215], v[228:231], v[64:67]
	v_mfma_f32_16x16x32_bf16 v[72:75], v[216:219], v[228:231], v[72:75]
	ds_read_b128 v[228:231], v166 offset:12288
	s_waitcnt lgkmcnt(3)
	v_mfma_f32_16x16x32_bf16 v[84:87], v[204:207], v[232:235], v[84:87]
	v_mfma_f32_16x16x32_bf16 v[92:95], v[208:211], v[232:235], v[92:95]
	v_mfma_f32_16x16x32_bf16 v[68:71], v[212:215], v[232:235], v[68:71]
	v_mfma_f32_16x16x32_bf16 v[76:79], v[216:219], v[232:235], v[76:79]
	ds_read_b128 v[232:235], v166 offset:14336
	s_waitcnt lgkmcnt(3)
	v_mfma_f32_16x16x32_bf16 v[48:51], v[204:207], v[220:223], v[48:51]
	v_mfma_f32_16x16x32_bf16 v[56:59], v[208:211], v[220:223], v[56:59]
	v_mfma_f32_16x16x32_bf16 v[32:35], v[212:215], v[220:223], v[32:35]
	v_mfma_f32_16x16x32_bf16 v[40:43], v[216:219], v[220:223], v[40:43]
	s_waitcnt lgkmcnt(2)
	v_mfma_f32_16x16x32_bf16 v[52:55], v[204:207], v[224:227], v[52:55]
	v_mfma_f32_16x16x32_bf16 v[60:63], v[208:211], v[224:227], v[60:63]
	v_mfma_f32_16x16x32_bf16 v[36:39], v[212:215], v[224:227], v[36:39]
	v_mfma_f32_16x16x32_bf16 v[44:47], v[216:219], v[224:227], v[44:47]
	s_waitcnt lgkmcnt(1)
	v_mfma_f32_16x16x32_bf16 v[16:19], v[204:207], v[228:231], v[16:19]
	v_mfma_f32_16x16x32_bf16 v[24:27], v[208:211], v[228:231], v[24:27]
	v_mfma_f32_16x16x32_bf16 v[0:3], v[212:215], v[228:231], v[0:3]
	v_mfma_f32_16x16x32_bf16 v[8:11], v[216:219], v[228:231], v[8:11]
	s_waitcnt lgkmcnt(0)
	s_add_u32 s28, s28, 0x80
	s_addc_u32 s29, s29, 0
	s_add_u32 s49, s49, 0x10000
	s_sub_u32 s53, s49, 0x28000
	s_cmp_ge_u32 s49, 0x28000
	s_cselect_b32 s49, s53, s49
	s_mov_b32 s50, s51
	s_waitcnt vmcnt(0)
	s_barrier
	v_add_u32_e32 v167, s50, v144
	v_add_u32_e32 v166, s49, v142
	ds_read_b128 v[188:191], v167
	ds_read_b128 v[192:195], v167 offset:2048
	ds_read_b128 v[196:199], v167 offset:4096
	ds_read_b128 v[200:203], v167 offset:6144
	ds_read_b128 v[220:223], v166
	ds_read_b128 v[224:227], v166 offset:2048
	ds_read_b128 v[228:231], v166 offset:4096
	v_mfma_f32_16x16x32_bf16 v[20:23], v[204:207], v[232:235], v[20:23]
	v_mfma_f32_16x16x32_bf16 v[28:31], v[208:211], v[232:235], v[28:31]
	v_mfma_f32_16x16x32_bf16 v[4:7], v[212:215], v[232:235], v[4:7]
	v_mfma_f32_16x16x32_bf16 v[12:15], v[216:219], v[232:235], v[12:15]
	ds_read_b128 v[232:235], v166 offset:6144
	v_add_u32_e32 v167, s50, v145
	s_waitcnt lgkmcnt(4)
	s_waitcnt lgkmcnt(3)
	v_mfma_f32_16x16x32_bf16 v[112:115], v[188:191], v[220:223], v[112:115]
	v_mfma_f32_16x16x32_bf16 v[120:123], v[192:195], v[220:223], v[120:123]
	v_mfma_f32_16x16x32_bf16 v[96:99], v[196:199], v[220:223], v[96:99]
	v_mfma_f32_16x16x32_bf16 v[104:107], v[200:203], v[220:223], v[104:107]
	ds_read_b128 v[220:223], v166 offset:8192
	ds_read_b128 v[204:207], v167
	s_waitcnt lgkmcnt(4)
	v_mfma_f32_16x16x32_bf16 v[116:119], v[188:191], v[224:227], v[116:119]
	v_mfma_f32_16x16x32_bf16 v[124:127], v[192:195], v[224:227], v[124:127]
	v_mfma_f32_16x16x32_bf16 v[100:103], v[196:199], v[224:227], v[100:103]
	v_mfma_f32_16x16x32_bf16 v[108:111], v[200:203], v[224:227], v[108:111]
	ds_read_b128 v[224:227], v166 offset:10240
	ds_read_b128 v[208:211], v167 offset:2048
	s_waitcnt lgkmcnt(5)
	v_mfma_f32_16x16x32_bf16 v[80:83], v[188:191], v[228:231], v[80:83]
	v_mfma_f32_16x16x32_bf16 v[88:91], v[192:195], v[228:231], v[88:91]
	v_mfma_f32_16x16x32_bf16 v[64:67], v[196:199], v[228:231], v[64:67]
	v_mfma_f32_16x16x32_bf16 v[72:75], v[200:203], v[228:231], v[72:75]
	ds_read_b128 v[228:231], v166 offset:12288
	ds_read_b128 v[212:215], v167 offset:4096
	s_waitcnt lgkmcnt(6)
	v_mfma_f32_16x16x32_bf16 v[84:87], v[188:191], v[232:235], v[84:87]
	v_mfma_f32_16x16x32_bf16 v[92:95], v[192:195], v[232:235], v[92:95]
	v_mfma_f32_16x16x32_bf16 v[68:71], v[196:199], v[232:235], v[68:71]
	v_mfma_f32_16x16x32_bf16 v[76:79], v[200:203], v[232:235], v[76:79]
	ds_read_b128 v[232:235], v166 offset:14336
	ds_read_b128 v[216:219], v167 offset:6144
	v_add_u32_e32 v166, s49, v143
	s_waitcnt lgkmcnt(7)
	v_mfma_f32_16x16x32_bf16 v[48:51], v[188:191], v[220:223], v[48:51]
	v_mfma_f32_16x16x32_bf16 v[56:59], v[192:195], v[220:223], v[56:59]
	v_mfma_f32_16x16x32_bf16 v[32:35], v[196:199], v[220:223], v[32:35]
	v_mfma_f32_16x16x32_bf16 v[40:43], v[200:203], v[220:223], v[40:43]
	ds_read_b128 v[220:223], v166
	s_waitcnt lgkmcnt(6)
	v_mfma_f32_16x16x32_bf16 v[52:55], v[188:191], v[224:227], v[52:55]
	v_mfma_f32_16x16x32_bf16 v[60:63], v[192:195], v[224:227], v[60:63]
	v_mfma_f32_16x16x32_bf16 v[36:39], v[196:199], v[224:227], v[36:39]
	v_mfma_f32_16x16x32_bf16 v[44:47], v[200:203], v[224:227], v[44:47]
	ds_read_b128 v[224:227], v166 offset:2048
	s_waitcnt lgkmcnt(5)
	v_mfma_f32_16x16x32_bf16 v[16:19], v[188:191], v[228:231], v[16:19]
	v_mfma_f32_16x16x32_bf16 v[24:27], v[192:195], v[228:231], v[24:27]
	v_mfma_f32_16x16x32_bf16 v[0:3], v[196:199], v[228:231], v[0:3]
	v_mfma_f32_16x16x32_bf16 v[8:11], v[200:203], v[228:231], v[8:11]
	ds_read_b128 v[228:231], v166 offset:4096
	s_waitcnt lgkmcnt(4)
	v_mfma_f32_16x16x32_bf16 v[20:23], v[188:191], v[232:235], v[20:23]
	v_mfma_f32_16x16x32_bf16 v[28:31], v[192:195], v[232:235], v[28:31]
	v_mfma_f32_16x16x32_bf16 v[4:7], v[196:199], v[232:235], v[4:7]
	v_mfma_f32_16x16x32_bf16 v[12:15], v[200:203], v[232:235], v[12:15]
	ds_read_b128 v[232:235], v166 offset:6144
	s_waitcnt lgkmcnt(4)
	s_waitcnt lgkmcnt(3)
	v_mfma_f32_16x16x32_bf16 v[112:115], v[204:207], v[220:223], v[112:115]
	v_mfma_f32_16x16x32_bf16 v[120:123], v[208:211], v[220:223], v[120:123]
	v_mfma_f32_16x16x32_bf16 v[96:99], v[212:215], v[220:223], v[96:99]
	v_mfma_f32_16x16x32_bf16 v[104:107], v[216:219], v[220:223], v[104:107]
	ds_read_b128 v[220:223], v166 offset:8192
	s_waitcnt lgkmcnt(3)
	v_mfma_f32_16x16x32_bf16 v[116:119], v[204:207], v[224:227], v[116:119]
	v_mfma_f32_16x16x32_bf16 v[124:127], v[208:211], v[224:227], v[124:127]
	v_mfma_f32_16x16x32_bf16 v[100:103], v[212:215], v[224:227], v[100:103]
	v_mfma_f32_16x16x32_bf16 v[108:111], v[216:219], v[224:227], v[108:111]
	ds_read_b128 v[224:227], v166 offset:10240
	s_waitcnt lgkmcnt(3)
	v_mfma_f32_16x16x32_bf16 v[80:83], v[204:207], v[228:231], v[80:83]
	v_mfma_f32_16x16x32_bf16 v[88:91], v[208:211], v[228:231], v[88:91]
	v_mfma_f32_16x16x32_bf16 v[64:67], v[212:215], v[228:231], v[64:67]
	v_mfma_f32_16x16x32_bf16 v[72:75], v[216:219], v[228:231], v[72:75]
	ds_read_b128 v[228:231], v166 offset:12288
	s_waitcnt lgkmcnt(3)
	v_mfma_f32_16x16x32_bf16 v[84:87], v[204:207], v[232:235], v[84:87]
	v_mfma_f32_16x16x32_bf16 v[92:95], v[208:211], v[232:235], v[92:95]
	v_mfma_f32_16x16x32_bf16 v[68:71], v[212:215], v[232:235], v[68:71]
	v_mfma_f32_16x16x32_bf16 v[76:79], v[216:219], v[232:235], v[76:79]
	ds_read_b128 v[232:235], v166 offset:14336
	s_waitcnt lgkmcnt(3)
	v_mfma_f32_16x16x32_bf16 v[48:51], v[204:207], v[220:223], v[48:51]
	v_mfma_f32_16x16x32_bf16 v[56:59], v[208:211], v[220:223], v[56:59]
	v_mfma_f32_16x16x32_bf16 v[32:35], v[212:215], v[220:223], v[32:35]
	v_mfma_f32_16x16x32_bf16 v[40:43], v[216:219], v[220:223], v[40:43]
	s_waitcnt lgkmcnt(2)
	v_mfma_f32_16x16x32_bf16 v[52:55], v[204:207], v[224:227], v[52:55]
	v_mfma_f32_16x16x32_bf16 v[60:63], v[208:211], v[224:227], v[60:63]
	v_mfma_f32_16x16x32_bf16 v[36:39], v[212:215], v[224:227], v[36:39]
	v_mfma_f32_16x16x32_bf16 v[44:47], v[216:219], v[224:227], v[44:47]
	s_waitcnt lgkmcnt(1)
	v_mfma_f32_16x16x32_bf16 v[16:19], v[204:207], v[228:231], v[16:19]
	v_mfma_f32_16x16x32_bf16 v[24:27], v[208:211], v[228:231], v[24:27]
	v_mfma_f32_16x16x32_bf16 v[0:3], v[212:215], v[228:231], v[0:3]
	v_mfma_f32_16x16x32_bf16 v[8:11], v[216:219], v[228:231], v[8:11]
	s_waitcnt lgkmcnt(0)
	s_waitcnt vmcnt(0)
	s_barrier
	v_mfma_f32_16x16x32_bf16 v[20:23], v[204:207], v[232:235], v[20:23]
	v_mfma_f32_16x16x32_bf16 v[28:31], v[208:211], v[232:235], v[28:31]
	v_mfma_f32_16x16x32_bf16 v[4:7], v[212:215], v[232:235], v[4:7]
	v_mfma_f32_16x16x32_bf16 v[12:15], v[216:219], v[232:235], v[12:15]
	s_nop 15
	v_permlane16_swap_b32_e32 v112, v116
	v_permlane16_swap_b32_e32 v113, v117
	v_permlane16_swap_b32_e32 v114, v118
	v_permlane16_swap_b32_e32 v115, v119
	v_permlane16_swap_b32_e32 v120, v124
	v_permlane16_swap_b32_e32 v121, v125
	v_permlane16_swap_b32_e32 v122, v126
	v_permlane16_swap_b32_e32 v123, v127
	v_permlane16_swap_b32_e32 v96, v100
	v_permlane16_swap_b32_e32 v97, v101
	v_permlane16_swap_b32_e32 v98, v102
	v_permlane16_swap_b32_e32 v99, v103
	v_permlane16_swap_b32_e32 v104, v108
	v_permlane16_swap_b32_e32 v105, v109
	v_permlane16_swap_b32_e32 v106, v110
	v_permlane16_swap_b32_e32 v107, v111
	v_permlane16_swap_b32_e32 v80, v84
	v_permlane16_swap_b32_e32 v81, v85
	v_permlane16_swap_b32_e32 v82, v86
	v_permlane16_swap_b32_e32 v83, v87
	v_permlane16_swap_b32_e32 v88, v92
	v_permlane16_swap_b32_e32 v89, v93
	v_permlane16_swap_b32_e32 v90, v94
	v_permlane16_swap_b32_e32 v91, v95
	v_permlane16_swap_b32_e32 v64, v68
	v_permlane16_swap_b32_e32 v65, v69
	v_permlane16_swap_b32_e32 v66, v70
	v_permlane16_swap_b32_e32 v67, v71
	v_permlane16_swap_b32_e32 v72, v76
	v_permlane16_swap_b32_e32 v73, v77
	v_permlane16_swap_b32_e32 v74, v78
	v_permlane16_swap_b32_e32 v75, v79
	v_permlane16_swap_b32_e32 v48, v52
	v_permlane16_swap_b32_e32 v49, v53
	v_permlane16_swap_b32_e32 v50, v54
	v_permlane16_swap_b32_e32 v51, v55
	v_permlane16_swap_b32_e32 v56, v60
	v_permlane16_swap_b32_e32 v57, v61
	v_permlane16_swap_b32_e32 v58, v62
	v_permlane16_swap_b32_e32 v59, v63
	v_permlane16_swap_b32_e32 v32, v36
	v_permlane16_swap_b32_e32 v33, v37
	v_permlane16_swap_b32_e32 v34, v38
	v_permlane16_swap_b32_e32 v35, v39
	v_permlane16_swap_b32_e32 v40, v44
	v_permlane16_swap_b32_e32 v41, v45
	v_permlane16_swap_b32_e32 v42, v46
	v_permlane16_swap_b32_e32 v43, v47
	v_permlane16_swap_b32_e32 v16, v20
	v_permlane16_swap_b32_e32 v17, v21
	v_permlane16_swap_b32_e32 v18, v22
	v_permlane16_swap_b32_e32 v19, v23
	v_permlane16_swap_b32_e32 v24, v28
	v_permlane16_swap_b32_e32 v25, v29
	v_permlane16_swap_b32_e32 v26, v30
	v_permlane16_swap_b32_e32 v27, v31
	v_permlane16_swap_b32_e32 v0, v4
	v_permlane16_swap_b32_e32 v1, v5
	v_permlane16_swap_b32_e32 v2, v6
	v_permlane16_swap_b32_e32 v3, v7
	v_permlane16_swap_b32_e32 v8, v12
	v_permlane16_swap_b32_e32 v9, v13
	v_permlane16_swap_b32_e32 v10, v14
	v_permlane16_swap_b32_e32 v11, v15
	v_permlane32_swap_b32_e32 v112, v116
	v_permlane32_swap_b32_e32 v113, v117
	v_permlane32_swap_b32_e32 v114, v118
	v_permlane32_swap_b32_e32 v115, v119
	v_permlane32_swap_b32_e32 v120, v124
	v_permlane32_swap_b32_e32 v121, v125
	v_permlane32_swap_b32_e32 v122, v126
	v_permlane32_swap_b32_e32 v123, v127
	v_permlane32_swap_b32_e32 v96, v100
	v_permlane32_swap_b32_e32 v97, v101
	v_permlane32_swap_b32_e32 v98, v102
	v_permlane32_swap_b32_e32 v99, v103
	v_permlane32_swap_b32_e32 v104, v108
	v_permlane32_swap_b32_e32 v105, v109
	v_permlane32_swap_b32_e32 v106, v110
	v_permlane32_swap_b32_e32 v107, v111
	v_permlane32_swap_b32_e32 v80, v84
	v_permlane32_swap_b32_e32 v81, v85
	v_permlane32_swap_b32_e32 v82, v86
	v_permlane32_swap_b32_e32 v83, v87
	v_permlane32_swap_b32_e32 v88, v92
	v_permlane32_swap_b32_e32 v89, v93
	v_permlane32_swap_b32_e32 v90, v94
	v_permlane32_swap_b32_e32 v91, v95
	v_permlane32_swap_b32_e32 v64, v68
	v_permlane32_swap_b32_e32 v65, v69
	v_permlane32_swap_b32_e32 v66, v70
	v_permlane32_swap_b32_e32 v67, v71
	v_permlane32_swap_b32_e32 v72, v76
	v_permlane32_swap_b32_e32 v73, v77
	v_permlane32_swap_b32_e32 v74, v78
	v_permlane32_swap_b32_e32 v75, v79
	v_permlane32_swap_b32_e32 v48, v52
	v_permlane32_swap_b32_e32 v49, v53
	v_permlane32_swap_b32_e32 v50, v54
	v_permlane32_swap_b32_e32 v51, v55
	v_permlane32_swap_b32_e32 v56, v60
	v_permlane32_swap_b32_e32 v57, v61
	v_permlane32_swap_b32_e32 v58, v62
	v_permlane32_swap_b32_e32 v59, v63
	v_permlane32_swap_b32_e32 v32, v36
	v_permlane32_swap_b32_e32 v33, v37
	v_permlane32_swap_b32_e32 v34, v38
	v_permlane32_swap_b32_e32 v35, v39
	v_permlane32_swap_b32_e32 v40, v44
	v_permlane32_swap_b32_e32 v41, v45
	v_permlane32_swap_b32_e32 v42, v46
	v_permlane32_swap_b32_e32 v43, v47
	v_permlane32_swap_b32_e32 v16, v20
	v_permlane32_swap_b32_e32 v17, v21
	v_permlane32_swap_b32_e32 v18, v22
	v_permlane32_swap_b32_e32 v19, v23
	v_permlane32_swap_b32_e32 v24, v28
	v_permlane32_swap_b32_e32 v25, v29
	v_permlane32_swap_b32_e32 v26, v30
	v_permlane32_swap_b32_e32 v27, v31
	v_permlane32_swap_b32_e32 v0, v4
	v_permlane32_swap_b32_e32 v1, v5
	v_permlane32_swap_b32_e32 v2, v6
	v_permlane32_swap_b32_e32 v3, v7
	v_permlane32_swap_b32_e32 v8, v12
	v_permlane32_swap_b32_e32 v9, v13
	v_permlane32_swap_b32_e32 v10, v14
	v_permlane32_swap_b32_e32 v11, v15
	s_nop 1
	s_branch .LBB0_163

.Lg163_loop:
	s_add_u32 s51, s50, 0x10000
	s_sub_u32 s53, s51, 0x28000
	s_cmp_ge_u32 s51, 0x28000
	s_cselect_b32 s51, s53, s51
	s_add_u32 s52, s49, 0x20000
	s_sub_u32 s53, s52, 0x28000
	s_cmp_ge_u32 s52, 0x28000
	s_cselect_b32 s52, s53, s52
	v_add_u32_e32 v246, s50, v244
	s_waitcnt lgkmcnt(4)
	s_waitcnt lgkmcnt(3)
	v_mfma_f32_16x16x32_bf16 v[112:115], v[192:195], v[224:227], v[112:115]
	v_mfma_f32_16x16x32_bf16 v[120:123], v[196:199], v[224:227], v[120:123]
	v_mfma_f32_16x16x32_bf16 v[96:99], v[200:203], v[224:227], v[96:99]
	v_mfma_f32_16x16x32_bf16 v[104:107], v[204:207], v[224:227], v[104:107]
	s_add_u32 m0, s51, s48
	s_nop 0
	global_load_lds_dwordx4 v248, s[64:65]
	s_add_u32 s64, s64, 0x80
	s_addc_u32 s65, s65, 0
	s_add_u32 s53, s51, s48
	s_add_u32 m0, s53, 0x2000
	s_nop 0
	global_load_lds_dwordx4 v248, s[66:67]
	s_add_u32 s66, s66, 0x80
	s_addc_u32 s67, s67, 0
	ds_read_b128 v[224:227], v245 offset:8192
	ds_read_b128 v[208:211], v246
	s_waitcnt lgkmcnt(4)
	v_mfma_f32_16x16x32_bf16 v[116:119], v[192:195], v[228:231], v[116:119]
	v_mfma_f32_16x16x32_bf16 v[124:127], v[196:199], v[228:231], v[124:127]
	v_mfma_f32_16x16x32_bf16 v[100:103], v[200:203], v[228:231], v[100:103]
	v_mfma_f32_16x16x32_bf16 v[108:111], v[204:207], v[228:231], v[108:111]
	s_add_u32 s53, s51, s48
	s_add_u32 m0, s53, 0x4000
	s_nop 0
	global_load_lds_dwordx4 v248, s[68:69]
	s_add_u32 s68, s68, 0x80
	s_addc_u32 s69, s69, 0
	s_add_u32 s53, s51, s48
	s_add_u32 m0, s53, 0x6000
	s_nop 0
	global_load_lds_dwordx4 v248, s[70:71]
	s_add_u32 s70, s70, 0x80
	s_addc_u32 s71, s71, 0
	ds_read_b128 v[228:231], v245 offset:10240
	ds_read_b128 v[212:215], v246 offset:2048
	s_waitcnt lgkmcnt(5)
	v_mfma_f32_16x16x32_bf16 v[80:83], v[192:195], v[232:235], v[80:83]
	v_mfma_f32_16x16x32_bf16 v[88:91], v[196:199], v[232:235], v[88:91]
	v_mfma_f32_16x16x32_bf16 v[64:67], v[200:203], v[232:235], v[64:67]
	v_mfma_f32_16x16x32_bf16 v[72:75], v[204:207], v[232:235], v[72:75]
	ds_read_b128 v[232:235], v245 offset:12288
	ds_read_b128 v[216:219], v246 offset:4096
	s_waitcnt lgkmcnt(6)
	v_mfma_f32_16x16x32_bf16 v[84:87], v[192:195], v[236:239], v[84:87]
	v_mfma_f32_16x16x32_bf16 v[92:95], v[196:199], v[236:239], v[92:95]
	v_mfma_f32_16x16x32_bf16 v[68:71], v[200:203], v[236:239], v[68:71]
	v_mfma_f32_16x16x32_bf16 v[76:79], v[204:207], v[236:239], v[76:79]
	ds_read_b128 v[236:239], v245 offset:14336
	ds_read_b128 v[220:223], v246 offset:6144
	v_add_u32_e32 v245, s49, v241
	s_waitcnt lgkmcnt(7)
	v_mfma_f32_16x16x32_bf16 v[48:51], v[192:195], v[224:227], v[48:51]
	v_mfma_f32_16x16x32_bf16 v[56:59], v[196:199], v[224:227], v[56:59]
	v_mfma_f32_16x16x32_bf16 v[32:35], v[200:203], v[224:227], v[32:35]
	v_mfma_f32_16x16x32_bf16 v[40:43], v[204:207], v[224:227], v[40:43]
	ds_read_b128 v[224:227], v245
	s_waitcnt lgkmcnt(6)
	v_mfma_f32_16x16x32_bf16 v[52:55], v[192:195], v[228:231], v[52:55]
	v_mfma_f32_16x16x32_bf16 v[60:63], v[196:199], v[228:231], v[60:63]
	v_mfma_f32_16x16x32_bf16 v[36:39], v[200:203], v[228:231], v[36:39]
	v_mfma_f32_16x16x32_bf16 v[44:47], v[204:207], v[228:231], v[44:47]
	ds_read_b128 v[228:231], v245 offset:2048
	s_waitcnt lgkmcnt(5)
	v_mfma_f32_16x16x32_bf16 v[16:19], v[192:195], v[232:235], v[16:19]
	v_mfma_f32_16x16x32_bf16 v[24:27], v[196:199], v[232:235], v[24:27]
	v_mfma_f32_16x16x32_bf16 v[0:3], v[200:203], v[232:235], v[0:3]
	v_mfma_f32_16x16x32_bf16 v[8:11], v[204:207], v[232:235], v[8:11]
	ds_read_b128 v[232:235], v245 offset:4096
	s_waitcnt lgkmcnt(4)
	v_mfma_f32_16x16x32_bf16 v[20:23], v[192:195], v[236:239], v[20:23]
	v_mfma_f32_16x16x32_bf16 v[28:31], v[196:199], v[236:239], v[28:31]
	v_mfma_f32_16x16x32_bf16 v[4:7], v[200:203], v[236:239], v[4:7]
	v_mfma_f32_16x16x32_bf16 v[12:15], v[204:207], v[236:239], v[12:15]
	ds_read_b128 v[236:239], v245 offset:6144
	s_waitcnt lgkmcnt(4)
	s_waitcnt lgkmcnt(3)
	v_mfma_f32_16x16x32_bf16 v[112:115], v[208:211], v[224:227], v[112:115]
	v_mfma_f32_16x16x32_bf16 v[120:123], v[212:215], v[224:227], v[120:123]
	v_mfma_f32_16x16x32_bf16 v[96:99], v[216:219], v[224:227], v[96:99]
	v_mfma_f32_16x16x32_bf16 v[104:107], v[220:223], v[224:227], v[104:107]
	ds_read_b128 v[224:227], v245 offset:8192
	s_waitcnt lgkmcnt(3)
	v_mfma_f32_16x16x32_bf16 v[116:119], v[208:211], v[228:231], v[116:119]
	v_mfma_f32_16x16x32_bf16 v[124:127], v[212:215], v[228:231], v[124:127]
	v_mfma_f32_16x16x32_bf16 v[100:103], v[216:219], v[228:231], v[100:103]
	v_mfma_f32_16x16x32_bf16 v[108:111], v[220:223], v[228:231], v[108:111]
	ds_read_b128 v[228:231], v245 offset:10240
	s_waitcnt lgkmcnt(3)
	v_mfma_f32_16x16x32_bf16 v[80:83], v[208:211], v[232:235], v[80:83]
	v_mfma_f32_16x16x32_bf16 v[88:91], v[212:215], v[232:235], v[88:91]
	v_mfma_f32_16x16x32_bf16 v[64:67], v[216:219], v[232:235], v[64:67]
	v_mfma_f32_16x16x32_bf16 v[72:75], v[220:223], v[232:235], v[72:75]
	ds_read_b128 v[232:235], v245 offset:12288
	s_waitcnt lgkmcnt(3)
	v_mfma_f32_16x16x32_bf16 v[84:87], v[208:211], v[236:239], v[84:87]
	v_mfma_f32_16x16x32_bf16 v[92:95], v[212:215], v[236:239], v[92:95]
	v_mfma_f32_16x16x32_bf16 v[68:71], v[216:219], v[236:239], v[68:71]
	v_mfma_f32_16x16x32_bf16 v[76:79], v[220:223], v[236:239], v[76:79]
	ds_read_b128 v[236:239], v245 offset:14336
	s_waitcnt lgkmcnt(3)
	v_mfma_f32_16x16x32_bf16 v[48:51], v[208:211], v[224:227], v[48:51]
	v_mfma_f32_16x16x32_bf16 v[56:59], v[212:215], v[224:227], v[56:59]
	v_mfma_f32_16x16x32_bf16 v[32:35], v[216:219], v[224:227], v[32:35]
	v_mfma_f32_16x16x32_bf16 v[40:43], v[220:223], v[224:227], v[40:43]
	s_waitcnt lgkmcnt(2)
	v_mfma_f32_16x16x32_bf16 v[52:55], v[208:211], v[228:231], v[52:55]
	v_mfma_f32_16x16x32_bf16 v[60:63], v[212:215], v[228:231], v[60:63]
	v_mfma_f32_16x16x32_bf16 v[36:39], v[216:219], v[228:231], v[36:39]
	v_mfma_f32_16x16x32_bf16 v[44:47], v[220:223], v[228:231], v[44:47]
	s_add_u32 m0, s52, s48
	s_nop 0
	global_load_lds_dwordx4 v247, s[56:57]
	s_add_u32 s56, s56, 0x80
	s_addc_u32 s57, s57, 0
	s_add_u32 s53, s52, s48
	s_add_u32 m0, s53, 0x2000
	s_nop 0
	global_load_lds_dwordx4 v247, s[58:59]
	s_add_u32 s58, s58, 0x80
	s_addc_u32 s59, s59, 0
	s_waitcnt lgkmcnt(1)
	v_mfma_f32_16x16x32_bf16 v[16:19], v[208:211], v[232:235], v[16:19]
	v_mfma_f32_16x16x32_bf16 v[24:27], v[212:215], v[232:235], v[24:27]
	v_mfma_f32_16x16x32_bf16 v[0:3], v[216:219], v[232:235], v[0:3]
	v_mfma_f32_16x16x32_bf16 v[8:11], v[220:223], v[232:235], v[8:11]
	s_add_u32 s53, s52, s48
	s_add_u32 m0, s53, 0x4000
	s_nop 0
	global_load_lds_dwordx4 v247, s[60:61]
	s_add_u32 s60, s60, 0x80
	s_addc_u32 s61, s61, 0
	s_add_u32 s53, s52, s48
	s_add_u32 m0, s53, 0x6000
	s_nop 0
	global_load_lds_dwordx4 v247, s[62:63]
	s_add_u32 s62, s62, 0x80
	s_addc_u32 s63, s63, 0
	s_waitcnt lgkmcnt(0)
	s_add_u32 s28, s28, 0x80
	s_addc_u32 s29, s29, 0
	s_add_u32 s49, s49, 0x10000
	s_sub_u32 s53, s49, 0x28000
	s_cmp_ge_u32 s49, 0x28000
	s_cselect_b32 s49, s53, s49
	s_mov_b32 s50, s51
	s_waitcnt vmcnt(4)
	s_barrier
	v_add_u32_e32 v246, s50, v243
	v_add_u32_e32 v245, s49, v240
	ds_read_b128 v[192:195], v246
	ds_read_b128 v[196:199], v246 offset:2048
	ds_read_b128 v[200:203], v246 offset:4096
	ds_read_b128 v[204:207], v246 offset:6144
	ds_read_b128 v[224:227], v245
	ds_read_b128 v[228:231], v245 offset:2048
	ds_read_b128 v[232:235], v245 offset:4096
	v_mfma_f32_16x16x32_bf16 v[20:23], v[208:211], v[236:239], v[20:23]
	v_mfma_f32_16x16x32_bf16 v[28:31], v[212:215], v[236:239], v[28:31]
	v_mfma_f32_16x16x32_bf16 v[4:7], v[216:219], v[236:239], v[4:7]
	v_mfma_f32_16x16x32_bf16 v[12:15], v[220:223], v[236:239], v[12:15]
	ds_read_b128 v[236:239], v245 offset:6144
	s_cmpk_lg_i32 s28, 0xf00
	s_cbranch_scc1 .Lg163_loop
	s_add_u32 s51, s50, 0x10000
	s_sub_u32 s53, s51, 0x28000
	s_cmp_ge_u32 s51, 0x28000
	s_cselect_b32 s51, s53, s51
	v_add_u32_e32 v246, s50, v244
	s_waitcnt lgkmcnt(4)
	s_waitcnt lgkmcnt(3)
	v_mfma_f32_16x16x32_bf16 v[112:115], v[192:195], v[224:227], v[112:115]
	v_mfma_f32_16x16x32_bf16 v[120:123], v[196:199], v[224:227], v[120:123]
	v_mfma_f32_16x16x32_bf16 v[96:99], v[200:203], v[224:227], v[96:99]
	v_mfma_f32_16x16x32_bf16 v[104:107], v[204:207], v[224:227], v[104:107]
	s_add_u32 m0, s51, s48
	s_nop 0
	global_load_lds_dwordx4 v248, s[64:65]
	s_add_u32 s64, s64, 0x80
	s_addc_u32 s65, s65, 0
	s_add_u32 s53, s51, s48
	s_add_u32 m0, s53, 0x2000
	s_nop 0
	global_load_lds_dwordx4 v248, s[66:67]
	s_add_u32 s66, s66, 0x80
	s_addc_u32 s67, s67, 0
	ds_read_b128 v[224:227], v245 offset:8192
	ds_read_b128 v[208:211], v246
	s_waitcnt lgkmcnt(4)
	v_mfma_f32_16x16x32_bf16 v[116:119], v[192:195], v[228:231], v[116:119]
	v_mfma_f32_16x16x32_bf16 v[124:127], v[196:199], v[228:231], v[124:127]
	v_mfma_f32_16x16x32_bf16 v[100:103], v[200:203], v[228:231], v[100:103]
	v_mfma_f32_16x16x32_bf16 v[108:111], v[204:207], v[228:231], v[108:111]
	s_add_u32 s53, s51, s48
	s_add_u32 m0, s53, 0x4000
	s_nop 0
	global_load_lds_dwordx4 v248, s[68:69]
	s_add_u32 s68, s68, 0x80
	s_addc_u32 s69, s69, 0
	s_add_u32 s53, s51, s48
	s_add_u32 m0, s53, 0x6000
	s_nop 0
	global_load_lds_dwordx4 v248, s[70:71]
	s_add_u32 s70, s70, 0x80
	s_addc_u32 s71, s71, 0
	ds_read_b128 v[228:231], v245 offset:10240
	ds_read_b128 v[212:215], v246 offset:2048
	s_waitcnt lgkmcnt(5)
	v_mfma_f32_16x16x32_bf16 v[80:83], v[192:195], v[232:235], v[80:83]
	v_mfma_f32_16x16x32_bf16 v[88:91], v[196:199], v[232:235], v[88:91]
	v_mfma_f32_16x16x32_bf16 v[64:67], v[200:203], v[232:235], v[64:67]
	v_mfma_f32_16x16x32_bf16 v[72:75], v[204:207], v[232:235], v[72:75]
	ds_read_b128 v[232:235], v245 offset:12288
	ds_read_b128 v[216:219], v246 offset:4096
	s_waitcnt lgkmcnt(6)
	v_mfma_f32_16x16x32_bf16 v[84:87], v[192:195], v[236:239], v[84:87]
	v_mfma_f32_16x16x32_bf16 v[92:95], v[196:199], v[236:239], v[92:95]
	v_mfma_f32_16x16x32_bf16 v[68:71], v[200:203], v[236:239], v[68:71]
	v_mfma_f32_16x16x32_bf16 v[76:79], v[204:207], v[236:239], v[76:79]
	ds_read_b128 v[236:239], v245 offset:14336
	ds_read_b128 v[220:223], v246 offset:6144
	v_add_u32_e32 v245, s49, v241
	s_waitcnt lgkmcnt(7)
	v_mfma_f32_16x16x32_bf16 v[48:51], v[192:195], v[224:227], v[48:51]
	v_mfma_f32_16x16x32_bf16 v[56:59], v[196:199], v[224:227], v[56:59]
	v_mfma_f32_16x16x32_bf16 v[32:35], v[200:203], v[224:227], v[32:35]
	v_mfma_f32_16x16x32_bf16 v[40:43], v[204:207], v[224:227], v[40:43]
	ds_read_b128 v[224:227], v245
	s_waitcnt lgkmcnt(6)
	v_mfma_f32_16x16x32_bf16 v[52:55], v[192:195], v[228:231], v[52:55]
	v_mfma_f32_16x16x32_bf16 v[60:63], v[196:199], v[228:231], v[60:63]
	v_mfma_f32_16x16x32_bf16 v[36:39], v[200:203], v[228:231], v[36:39]
	v_mfma_f32_16x16x32_bf16 v[44:47], v[204:207], v[228:231], v[44:47]
	ds_read_b128 v[228:231], v245 offset:2048
	s_waitcnt lgkmcnt(5)
	v_mfma_f32_16x16x32_bf16 v[16:19], v[192:195], v[232:235], v[16:19]
	v_mfma_f32_16x16x32_bf16 v[24:27], v[196:199], v[232:235], v[24:27]
	v_mfma_f32_16x16x32_bf16 v[0:3], v[200:203], v[232:235], v[0:3]
	v_mfma_f32_16x16x32_bf16 v[8:11], v[204:207], v[232:235], v[8:11]
	ds_read_b128 v[232:235], v245 offset:4096
	s_waitcnt lgkmcnt(4)
	v_mfma_f32_16x16x32_bf16 v[20:23], v[192:195], v[236:239], v[20:23]
	v_mfma_f32_16x16x32_bf16 v[28:31], v[196:199], v[236:239], v[28:31]
	v_mfma_f32_16x16x32_bf16 v[4:7], v[200:203], v[236:239], v[4:7]
	v_mfma_f32_16x16x32_bf16 v[12:15], v[204:207], v[236:239], v[12:15]
	ds_read_b128 v[236:239], v245 offset:6144
	s_waitcnt lgkmcnt(4)
	s_waitcnt lgkmcnt(3)
	v_mfma_f32_16x16x32_bf16 v[112:115], v[208:211], v[224:227], v[112:115]
	v_mfma_f32_16x16x32_bf16 v[120:123], v[212:215], v[224:227], v[120:123]
	v_mfma_f32_16x16x32_bf16 v[96:99], v[216:219], v[224:227], v[96:99]
	v_mfma_f32_16x16x32_bf16 v[104:107], v[220:223], v[224:227], v[104:107]
	ds_read_b128 v[224:227], v245 offset:8192
	s_waitcnt lgkmcnt(3)
	v_mfma_f32_16x16x32_bf16 v[116:119], v[208:211], v[228:231], v[116:119]
	v_mfma_f32_16x16x32_bf16 v[124:127], v[212:215], v[228:231], v[124:127]
	v_mfma_f32_16x16x32_bf16 v[100:103], v[216:219], v[228:231], v[100:103]
	v_mfma_f32_16x16x32_bf16 v[108:111], v[220:223], v[228:231], v[108:111]
	ds_read_b128 v[228:231], v245 offset:10240
	s_waitcnt lgkmcnt(3)
	v_mfma_f32_16x16x32_bf16 v[80:83], v[208:211], v[232:235], v[80:83]
	v_mfma_f32_16x16x32_bf16 v[88:91], v[212:215], v[232:235], v[88:91]
	v_mfma_f32_16x16x32_bf16 v[64:67], v[216:219], v[232:235], v[64:67]
	v_mfma_f32_16x16x32_bf16 v[72:75], v[220:223], v[232:235], v[72:75]
	ds_read_b128 v[232:235], v245 offset:12288
	s_waitcnt lgkmcnt(3)
	v_mfma_f32_16x16x32_bf16 v[84:87], v[208:211], v[236:239], v[84:87]
	v_mfma_f32_16x16x32_bf16 v[92:95], v[212:215], v[236:239], v[92:95]
	v_mfma_f32_16x16x32_bf16 v[68:71], v[216:219], v[236:239], v[68:71]
	v_mfma_f32_16x16x32_bf16 v[76:79], v[220:223], v[236:239], v[76:79]
	ds_read_b128 v[236:239], v245 offset:14336
	s_waitcnt lgkmcnt(3)
	v_mfma_f32_16x16x32_bf16 v[48:51], v[208:211], v[224:227], v[48:51]
	v_mfma_f32_16x16x32_bf16 v[56:59], v[212:215], v[224:227], v[56:59]
	v_mfma_f32_16x16x32_bf16 v[32:35], v[216:219], v[224:227], v[32:35]
	v_mfma_f32_16x16x32_bf16 v[40:43], v[220:223], v[224:227], v[40:43]
	s_waitcnt lgkmcnt(2)
	v_mfma_f32_16x16x32_bf16 v[52:55], v[208:211], v[228:231], v[52:55]
	v_mfma_f32_16x16x32_bf16 v[60:63], v[212:215], v[228:231], v[60:63]
	v_mfma_f32_16x16x32_bf16 v[36:39], v[216:219], v[228:231], v[36:39]
	v_mfma_f32_16x16x32_bf16 v[44:47], v[220:223], v[228:231], v[44:47]
	s_waitcnt lgkmcnt(1)
	v_mfma_f32_16x16x32_bf16 v[16:19], v[208:211], v[232:235], v[16:19]
	v_mfma_f32_16x16x32_bf16 v[24:27], v[212:215], v[232:235], v[24:27]
	v_mfma_f32_16x16x32_bf16 v[0:3], v[216:219], v[232:235], v[0:3]
	v_mfma_f32_16x16x32_bf16 v[8:11], v[220:223], v[232:235], v[8:11]
	s_waitcnt lgkmcnt(0)
	s_add_u32 s28, s28, 0x80
	s_addc_u32 s29, s29, 0
	s_add_u32 s49, s49, 0x10000
	s_sub_u32 s53, s49, 0x28000
	s_cmp_ge_u32 s49, 0x28000
	s_cselect_b32 s49, s53, s49
	s_mov_b32 s50, s51
	s_waitcnt vmcnt(0)
	s_barrier
	v_add_u32_e32 v246, s50, v243
	v_add_u32_e32 v245, s49, v240
	ds_read_b128 v[192:195], v246
	ds_read_b128 v[196:199], v246 offset:2048
	ds_read_b128 v[200:203], v246 offset:4096
	ds_read_b128 v[204:207], v246 offset:6144
	ds_read_b128 v[224:227], v245
	ds_read_b128 v[228:231], v245 offset:2048
	ds_read_b128 v[232:235], v245 offset:4096
	v_mfma_f32_16x16x32_bf16 v[20:23], v[208:211], v[236:239], v[20:23]
	v_mfma_f32_16x16x32_bf16 v[28:31], v[212:215], v[236:239], v[28:31]
	v_mfma_f32_16x16x32_bf16 v[4:7], v[216:219], v[236:239], v[4:7]
	v_mfma_f32_16x16x32_bf16 v[12:15], v[220:223], v[236:239], v[12:15]
	ds_read_b128 v[236:239], v245 offset:6144
	v_add_u32_e32 v246, s50, v244
	s_waitcnt lgkmcnt(4)
	s_waitcnt lgkmcnt(3)
	v_mfma_f32_16x16x32_bf16 v[112:115], v[192:195], v[224:227], v[112:115]
	v_mfma_f32_16x16x32_bf16 v[120:123], v[196:199], v[224:227], v[120:123]
	v_mfma_f32_16x16x32_bf16 v[96:99], v[200:203], v[224:227], v[96:99]
	v_mfma_f32_16x16x32_bf16 v[104:107], v[204:207], v[224:227], v[104:107]
	ds_read_b128 v[224:227], v245 offset:8192
	ds_read_b128 v[208:211], v246
	s_waitcnt lgkmcnt(4)
	v_mfma_f32_16x16x32_bf16 v[116:119], v[192:195], v[228:231], v[116:119]
	v_mfma_f32_16x16x32_bf16 v[124:127], v[196:199], v[228:231], v[124:127]
	v_mfma_f32_16x16x32_bf16 v[100:103], v[200:203], v[228:231], v[100:103]
	v_mfma_f32_16x16x32_bf16 v[108:111], v[204:207], v[228:231], v[108:111]
	ds_read_b128 v[228:231], v245 offset:10240
	ds_read_b128 v[212:215], v246 offset:2048
	s_waitcnt lgkmcnt(5)
	v_mfma_f32_16x16x32_bf16 v[80:83], v[192:195], v[232:235], v[80:83]
	v_mfma_f32_16x16x32_bf16 v[88:91], v[196:199], v[232:235], v[88:91]
	v_mfma_f32_16x16x32_bf16 v[64:67], v[200:203], v[232:235], v[64:67]
	v_mfma_f32_16x16x32_bf16 v[72:75], v[204:207], v[232:235], v[72:75]
	ds_read_b128 v[232:235], v245 offset:12288
	ds_read_b128 v[216:219], v246 offset:4096
	s_waitcnt lgkmcnt(6)
	v_mfma_f32_16x16x32_bf16 v[84:87], v[192:195], v[236:239], v[84:87]
	v_mfma_f32_16x16x32_bf16 v[92:95], v[196:199], v[236:239], v[92:95]
	v_mfma_f32_16x16x32_bf16 v[68:71], v[200:203], v[236:239], v[68:71]
	v_mfma_f32_16x16x32_bf16 v[76:79], v[204:207], v[236:239], v[76:79]
	ds_read_b128 v[236:239], v245 offset:14336
	ds_read_b128 v[220:223], v246 offset:6144
	v_add_u32_e32 v245, s49, v241
	s_waitcnt lgkmcnt(7)
	v_mfma_f32_16x16x32_bf16 v[48:51], v[192:195], v[224:227], v[48:51]
	v_mfma_f32_16x16x32_bf16 v[56:59], v[196:199], v[224:227], v[56:59]
	v_mfma_f32_16x16x32_bf16 v[32:35], v[200:203], v[224:227], v[32:35]
	v_mfma_f32_16x16x32_bf16 v[40:43], v[204:207], v[224:227], v[40:43]
	ds_read_b128 v[224:227], v245
	s_waitcnt lgkmcnt(6)
	v_mfma_f32_16x16x32_bf16 v[52:55], v[192:195], v[228:231], v[52:55]
	v_mfma_f32_16x16x32_bf16 v[60:63], v[196:199], v[228:231], v[60:63]
	v_mfma_f32_16x16x32_bf16 v[36:39], v[200:203], v[228:231], v[36:39]
	v_mfma_f32_16x16x32_bf16 v[44:47], v[204:207], v[228:231], v[44:47]
	ds_read_b128 v[228:231], v245 offset:2048
	s_waitcnt lgkmcnt(5)
	v_mfma_f32_16x16x32_bf16 v[16:19], v[192:195], v[232:235], v[16:19]
	v_mfma_f32_16x16x32_bf16 v[24:27], v[196:199], v[232:235], v[24:27]
	v_mfma_f32_16x16x32_bf16 v[0:3], v[200:203], v[232:235], v[0:3]
	v_mfma_f32_16x16x32_bf16 v[8:11], v[204:207], v[232:235], v[8:11]
	ds_read_b128 v[232:235], v245 offset:4096
	s_waitcnt lgkmcnt(4)
	v_mfma_f32_16x16x32_bf16 v[20:23], v[192:195], v[236:239], v[20:23]
	v_mfma_f32_16x16x32_bf16 v[28:31], v[196:199], v[236:239], v[28:31]
	v_mfma_f32_16x16x32_bf16 v[4:7], v[200:203], v[236:239], v[4:7]
	v_mfma_f32_16x16x32_bf16 v[12:15], v[204:207], v[236:239], v[12:15]
	ds_read_b128 v[236:239], v245 offset:6144
	s_waitcnt lgkmcnt(4)
	s_waitcnt lgkmcnt(3)
	v_mfma_f32_16x16x32_bf16 v[112:115], v[208:211], v[224:227], v[112:115]
	v_mfma_f32_16x16x32_bf16 v[120:123], v[212:215], v[224:227], v[120:123]
	v_mfma_f32_16x16x32_bf16 v[96:99], v[216:219], v[224:227], v[96:99]
	v_mfma_f32_16x16x32_bf16 v[104:107], v[220:223], v[224:227], v[104:107]
	ds_read_b128 v[224:227], v245 offset:8192
	s_waitcnt lgkmcnt(3)
	v_mfma_f32_16x16x32_bf16 v[116:119], v[208:211], v[228:231], v[116:119]
	v_mfma_f32_16x16x32_bf16 v[124:127], v[212:215], v[228:231], v[124:127]
	v_mfma_f32_16x16x32_bf16 v[100:103], v[216:219], v[228:231], v[100:103]
	v_mfma_f32_16x16x32_bf16 v[108:111], v[220:223], v[228:231], v[108:111]
	ds_read_b128 v[228:231], v245 offset:10240
	s_waitcnt lgkmcnt(3)
	v_mfma_f32_16x16x32_bf16 v[80:83], v[208:211], v[232:235], v[80:83]
	v_mfma_f32_16x16x32_bf16 v[88:91], v[212:215], v[232:235], v[88:91]
	v_mfma_f32_16x16x32_bf16 v[64:67], v[216:219], v[232:235], v[64:67]
	v_mfma_f32_16x16x32_bf16 v[72:75], v[220:223], v[232:235], v[72:75]
	ds_read_b128 v[232:235], v245 offset:12288
	s_waitcnt lgkmcnt(3)
	v_mfma_f32_16x16x32_bf16 v[84:87], v[208:211], v[236:239], v[84:87]
	v_mfma_f32_16x16x32_bf16 v[92:95], v[212:215], v[236:239], v[92:95]
	v_mfma_f32_16x16x32_bf16 v[68:71], v[216:219], v[236:239], v[68:71]
	v_mfma_f32_16x16x32_bf16 v[76:79], v[220:223], v[236:239], v[76:79]
	ds_read_b128 v[236:239], v245 offset:14336
	s_waitcnt lgkmcnt(3)
	v_mfma_f32_16x16x32_bf16 v[48:51], v[208:211], v[224:227], v[48:51]
	v_mfma_f32_16x16x32_bf16 v[56:59], v[212:215], v[224:227], v[56:59]
	v_mfma_f32_16x16x32_bf16 v[32:35], v[216:219], v[224:227], v[32:35]
	v_mfma_f32_16x16x32_bf16 v[40:43], v[220:223], v[224:227], v[40:43]
	s_waitcnt lgkmcnt(2)
	v_mfma_f32_16x16x32_bf16 v[52:55], v[208:211], v[228:231], v[52:55]
	v_mfma_f32_16x16x32_bf16 v[60:63], v[212:215], v[228:231], v[60:63]
	v_mfma_f32_16x16x32_bf16 v[36:39], v[216:219], v[228:231], v[36:39]
	v_mfma_f32_16x16x32_bf16 v[44:47], v[220:223], v[228:231], v[44:47]
	s_waitcnt lgkmcnt(1)
	v_mfma_f32_16x16x32_bf16 v[16:19], v[208:211], v[232:235], v[16:19]
	v_mfma_f32_16x16x32_bf16 v[24:27], v[212:215], v[232:235], v[24:27]
	v_mfma_f32_16x16x32_bf16 v[0:3], v[216:219], v[232:235], v[0:3]
	v_mfma_f32_16x16x32_bf16 v[8:11], v[220:223], v[232:235], v[8:11]
	s_waitcnt lgkmcnt(0)
	s_waitcnt vmcnt(0)
	s_barrier
	v_mfma_f32_16x16x32_bf16 v[20:23], v[208:211], v[236:239], v[20:23]
	v_mfma_f32_16x16x32_bf16 v[28:31], v[212:215], v[236:239], v[28:31]
	v_mfma_f32_16x16x32_bf16 v[4:7], v[216:219], v[236:239], v[4:7]
	v_mfma_f32_16x16x32_bf16 v[12:15], v[220:223], v[236:239], v[12:15]
	s_nop 15
	v_permlane16_swap_b32_e32 v112, v116
	v_permlane16_swap_b32_e32 v113, v117
	v_permlane16_swap_b32_e32 v114, v118
	v_permlane16_swap_b32_e32 v115, v119
	v_permlane16_swap_b32_e32 v120, v124
	v_permlane16_swap_b32_e32 v121, v125
	v_permlane16_swap_b32_e32 v122, v126
	v_permlane16_swap_b32_e32 v123, v127
	v_permlane16_swap_b32_e32 v96, v100
	v_permlane16_swap_b32_e32 v97, v101
	v_permlane16_swap_b32_e32 v98, v102
	v_permlane16_swap_b32_e32 v99, v103
	v_permlane16_swap_b32_e32 v104, v108
	v_permlane16_swap_b32_e32 v105, v109
	v_permlane16_swap_b32_e32 v106, v110
	v_permlane16_swap_b32_e32 v107, v111
	v_permlane16_swap_b32_e32 v80, v84
	v_permlane16_swap_b32_e32 v81, v85
	v_permlane16_swap_b32_e32 v82, v86
	v_permlane16_swap_b32_e32 v83, v87
	v_permlane16_swap_b32_e32 v88, v92
	v_permlane16_swap_b32_e32 v89, v93
	v_permlane16_swap_b32_e32 v90, v94
	v_permlane16_swap_b32_e32 v91, v95
	v_permlane16_swap_b32_e32 v64, v68
	v_permlane16_swap_b32_e32 v65, v69
	v_permlane16_swap_b32_e32 v66, v70
	v_permlane16_swap_b32_e32 v67, v71
	v_permlane16_swap_b32_e32 v72, v76
	v_permlane16_swap_b32_e32 v73, v77
	v_permlane16_swap_b32_e32 v74, v78
	v_permlane16_swap_b32_e32 v75, v79
	v_permlane16_swap_b32_e32 v48, v52
	v_permlane16_swap_b32_e32 v49, v53
	v_permlane16_swap_b32_e32 v50, v54
	v_permlane16_swap_b32_e32 v51, v55
	v_permlane16_swap_b32_e32 v56, v60
	v_permlane16_swap_b32_e32 v57, v61
	v_permlane16_swap_b32_e32 v58, v62
	v_permlane16_swap_b32_e32 v59, v63
	v_permlane16_swap_b32_e32 v32, v36
	v_permlane16_swap_b32_e32 v33, v37
	v_permlane16_swap_b32_e32 v34, v38
	v_permlane16_swap_b32_e32 v35, v39
	v_permlane16_swap_b32_e32 v40, v44
	v_permlane16_swap_b32_e32 v41, v45
	v_permlane16_swap_b32_e32 v42, v46
	v_permlane16_swap_b32_e32 v43, v47
	v_permlane16_swap_b32_e32 v16, v20
	v_permlane16_swap_b32_e32 v17, v21
	v_permlane16_swap_b32_e32 v18, v22
	v_permlane16_swap_b32_e32 v19, v23
	v_permlane16_swap_b32_e32 v24, v28
	v_permlane16_swap_b32_e32 v25, v29
	v_permlane16_swap_b32_e32 v26, v30
	v_permlane16_swap_b32_e32 v27, v31
	v_permlane16_swap_b32_e32 v0, v4
	v_permlane16_swap_b32_e32 v1, v5
	v_permlane16_swap_b32_e32 v2, v6
	v_permlane16_swap_b32_e32 v3, v7
	v_permlane16_swap_b32_e32 v8, v12
	v_permlane16_swap_b32_e32 v9, v13
	v_permlane16_swap_b32_e32 v10, v14
	v_permlane16_swap_b32_e32 v11, v15
	v_permlane32_swap_b32_e32 v112, v116
	v_permlane32_swap_b32_e32 v113, v117
	v_permlane32_swap_b32_e32 v114, v118
	v_permlane32_swap_b32_e32 v115, v119
	v_permlane32_swap_b32_e32 v120, v124
	v_permlane32_swap_b32_e32 v121, v125
	v_permlane32_swap_b32_e32 v122, v126
	v_permlane32_swap_b32_e32 v123, v127
	v_permlane32_swap_b32_e32 v96, v100
	v_permlane32_swap_b32_e32 v97, v101
	v_permlane32_swap_b32_e32 v98, v102
	v_permlane32_swap_b32_e32 v99, v103
	v_permlane32_swap_b32_e32 v104, v108
	v_permlane32_swap_b32_e32 v105, v109
	v_permlane32_swap_b32_e32 v106, v110
	v_permlane32_swap_b32_e32 v107, v111
	v_permlane32_swap_b32_e32 v80, v84
	v_permlane32_swap_b32_e32 v81, v85
	v_permlane32_swap_b32_e32 v82, v86
	v_permlane32_swap_b32_e32 v83, v87
	v_permlane32_swap_b32_e32 v88, v92
	v_permlane32_swap_b32_e32 v89, v93
	v_permlane32_swap_b32_e32 v90, v94
	v_permlane32_swap_b32_e32 v91, v95
	v_permlane32_swap_b32_e32 v64, v68
	v_permlane32_swap_b32_e32 v65, v69
	v_permlane32_swap_b32_e32 v66, v70
	v_permlane32_swap_b32_e32 v67, v71
	v_permlane32_swap_b32_e32 v72, v76
	v_permlane32_swap_b32_e32 v73, v77
	v_permlane32_swap_b32_e32 v74, v78
	v_permlane32_swap_b32_e32 v75, v79
	v_permlane32_swap_b32_e32 v48, v52
	v_permlane32_swap_b32_e32 v49, v53
	v_permlane32_swap_b32_e32 v50, v54
	v_permlane32_swap_b32_e32 v51, v55
	v_permlane32_swap_b32_e32 v56, v60
	v_permlane32_swap_b32_e32 v57, v61
	v_permlane32_swap_b32_e32 v58, v62
	v_permlane32_swap_b32_e32 v59, v63
	v_permlane32_swap_b32_e32 v32, v36
	v_permlane32_swap_b32_e32 v33, v37
	v_permlane32_swap_b32_e32 v34, v38
	v_permlane32_swap_b32_e32 v35, v39
	v_permlane32_swap_b32_e32 v40, v44
	v_permlane32_swap_b32_e32 v41, v45
	v_permlane32_swap_b32_e32 v42, v46
	v_permlane32_swap_b32_e32 v43, v47
	v_permlane32_swap_b32_e32 v16, v20
	v_permlane32_swap_b32_e32 v17, v21
	v_permlane32_swap_b32_e32 v18, v22
	v_permlane32_swap_b32_e32 v19, v23
	v_permlane32_swap_b32_e32 v24, v28
	v_permlane32_swap_b32_e32 v25, v29
	v_permlane32_swap_b32_e32 v26, v30
	v_permlane32_swap_b32_e32 v27, v31
	v_permlane32_swap_b32_e32 v0, v4
	v_permlane32_swap_b32_e32 v1, v5
	v_permlane32_swap_b32_e32 v2, v6
	v_permlane32_swap_b32_e32 v3, v7
	v_permlane32_swap_b32_e32 v8, v12
	v_permlane32_swap_b32_e32 v9, v13
	v_permlane32_swap_b32_e32 v10, v14
	v_permlane32_swap_b32_e32 v11, v15
	s_nop 1
